# v70 + scan loops: v_pk_mul_f32 state-tile scaling between MFMAs split into two v_mul_f32_e32 each (asm guide 7.5), bit-identical
# speedup vs baseline: 1.0010x; 1.0010x over previous
; __device__ __forceinline__ void scan_phase(const Frame& F, const bf16_t* Q, const bf16_t* K, const bf16_t* V, const bf16_t* PB, bf16_t* OF, bf16_t* OB, int half) {
;     ...
;                 {
;                     bf16x8 Rf[2];
; #pragma unroll
;                     for (int ks = 0; ks < 2; ++ks) { const f32x4 r0v = Rt[4 * p + 2 * ks], r1v = Rt[4 * p + 2 * ks + 1];
;                         const u32x4 wvv = {cvt_pk_bf16(r0v[0], r0v[1]), cvt_pk_bf16(r0v[2], r0v[3]), cvt_pk_bf16(r1v[0], r1v[1]), cvt_pk_bf16(r1v[2], r1v[3])};
;                         Rf[ks] = __builtin_bit_cast(bf16x8, wvv); }
;                     u32x4 qf[2][2];
;     ...
;                     SCAN_QREAD(0, 0);
; #pragma unroll
;                     for (int it = 0; it < 8; ++it) { if (it < 7) SCAN_QREAD((it + 1) & 1, it + 1);
; #pragma unroll
;                         for (int ks = 0; ks < 2; ++ks) Ot[it] = __builtin_amdgcn_mfma_f32_16x16x32_bf16(Rf[ks], __builtin_bit_cast(bf16x8, qf[it & 1][ks]), Ot[it], 0, 0, 0); }
;     ...
;                     __builtin_amdgcn_sched_group_barrier(0x100, 4, 0);
;                     __builtin_amdgcn_sched_group_barrier(0x100, 4, 0); __builtin_amdgcn_sched_group_barrier(0x8, 2, 0);
;                     __builtin_amdgcn_sched_group_barrier(0x100, 4, 0); __builtin_amdgcn_sched_group_barrier(0x8, 2, 0);
;                     __builtin_amdgcn_sched_group_barrier(0x100, 4, 0); __builtin_amdgcn_sched_group_barrier(0x8, 2, 0);
;                     __builtin_amdgcn_sched_group_barrier(0x100, 4, 0); __builtin_amdgcn_sched_group_barrier(0x8, 2, 0);
;                     __builtin_amdgcn_sched_group_barrier(0x100, 4, 0); __builtin_amdgcn_sched_group_barrier(0x8, 2, 0);
;                     __builtin_amdgcn_sched_group_barrier(0x100, 4, 0); __builtin_amdgcn_sched_group_barrier(0x8, 2, 0);
;                     __builtin_amdgcn_sched_group_barrier(0x100, 4, 0); __builtin_amdgcn_sched_group_barrier(0x8, 2, 0);
;                     __builtin_amdgcn_sched_group_barrier(0x8, 2, 0);
;                 }
;                 __builtin_amdgcn_sched_barrier(0);
;                 { s16x4 kl[2][4], kh[2][4];
;     ...
;                 SCAN_KREAD(0, 0);
; #pragma unroll
;                 for (int mt = 0; mt < 4; ++mt) { if (mt < 3) SCAN_KREAD((mt + 1) & 1, mt + 1);
;                     f32x4 acc = Rt[4 * p + mt] * c1;
; #pragma unroll
.LBB0_977:
	v_sub_u32_e32 v128, 0x80, v192
	v_cvt_f32_i32_e32 v238, v128
	v_cvt_pk_bf16_f32 v136, v48, v49
	v_cvt_pk_bf16_f32 v137, v50, v51
	v_cvt_pk_bf16_f32 v138, v52, v53
	v_cvt_pk_bf16_f32 v139, v54, v55
	v_cvt_pk_bf16_f32 v140, v56, v57
	v_cvt_pk_bf16_f32 v141, v58, v59
	v_cvt_pk_bf16_f32 v142, v60, v61
	v_cvt_pk_bf16_f32 v143, v62, v63
	ds_read_b64 v[128:129], v223 offset:16384
	ds_read_b64 v[130:131], v224 offset:16384
	ds_read_b64 v[132:133], v225 offset:16384
	ds_read_b64 v[134:135], v226 offset:16384
	ds_read_b64 v[156:157], v223 offset:18432
	ds_read_b64 v[158:159], v224 offset:18432
	ds_read_b64 v[194:195], v225 offset:18432
	ds_read_b64 v[196:197], v226 offset:18432
	s_waitcnt lgkmcnt(6)
	v_mfma_f32_16x16x32_bf16 v[96:99], v[136:139], v[128:131], v[96:99]
	s_waitcnt lgkmcnt(4)
	v_mfma_f32_16x16x32_bf16 v[128:131], v[140:143], v[132:135], v[96:99]
	s_nop 5
	ds_read_b64 v[96:97], v223 offset:20480
	ds_read_b64 v[98:99], v224 offset:20480
	ds_read_b64 v[234:235], v225 offset:20480
	ds_read_b64 v[236:237], v226 offset:20480
	s_waitcnt lgkmcnt(6)
	v_mfma_f32_16x16x32_bf16 v[100:103], v[136:139], v[156:159], v[100:103]
	s_waitcnt lgkmcnt(4)
	v_mfma_f32_16x16x32_bf16 v[132:135], v[140:143], v[194:197], v[100:103]
	s_nop 5
	ds_read_b64 v[100:101], v223 offset:22528
	ds_read_b64 v[102:103], v224 offset:22528
	ds_read_b64 v[156:157], v225 offset:22528
	ds_read_b64 v[158:159], v226 offset:22528
	s_waitcnt lgkmcnt(6)
	v_mfma_f32_16x16x32_bf16 v[96:99], v[136:139], v[96:99], v[104:107]
	s_waitcnt lgkmcnt(4)
	v_mfma_f32_16x16x32_bf16 v[104:107], v[140:143], v[234:237], v[96:99]
	s_nop 5
	ds_read_b64 v[96:97], v223 offset:24576
	ds_read_b64 v[98:99], v224 offset:24576
	ds_read_b64 v[194:195], v225 offset:24576
	ds_read_b64 v[196:197], v226 offset:24576
	s_waitcnt lgkmcnt(6)
	v_mfma_f32_16x16x32_bf16 v[100:103], v[136:139], v[100:103], v[108:111]
	s_waitcnt lgkmcnt(4)
	v_mfma_f32_16x16x32_bf16 v[108:111], v[140:143], v[156:159], v[100:103]
	s_nop 5
	ds_read_b64 v[100:101], v223 offset:26624
	ds_read_b64 v[102:103], v224 offset:26624
	ds_read_b64 v[156:157], v225 offset:26624
	ds_read_b64 v[158:159], v226 offset:26624
	s_waitcnt lgkmcnt(6)
	v_mfma_f32_16x16x32_bf16 v[96:99], v[136:139], v[96:99], v[112:115]
	s_waitcnt lgkmcnt(4)
	v_mfma_f32_16x16x32_bf16 v[112:115], v[140:143], v[194:197], v[96:99]
	s_nop 5
	ds_read_b64 v[96:97], v223 offset:28672
	ds_read_b64 v[98:99], v224 offset:28672
	ds_read_b64 v[194:195], v225 offset:28672
	ds_read_b64 v[196:197], v226 offset:28672
	s_waitcnt lgkmcnt(6)
	v_mfma_f32_16x16x32_bf16 v[100:103], v[136:139], v[100:103], v[116:119]
	s_waitcnt lgkmcnt(4)
	v_mfma_f32_16x16x32_bf16 v[100:103], v[140:143], v[156:159], v[100:103]
	s_nop 0
	ds_read_b64 v[116:117], v223 offset:30720
	ds_read_b64 v[118:119], v224 offset:30720
	ds_read_b64 v[156:157], v225 offset:30720
	ds_read_b64 v[158:159], v226 offset:30720
	s_waitcnt lgkmcnt(6)
	v_mfma_f32_16x16x32_bf16 v[96:99], v[136:139], v[96:99], v[120:123]
	s_waitcnt lgkmcnt(4)
	v_mfma_f32_16x16x32_bf16 v[96:99], v[140:143], v[194:197], v[96:99]
	s_waitcnt lgkmcnt(2)
	v_mfma_f32_16x16x32_bf16 v[116:119], v[136:139], v[116:119], v[124:127]
	s_waitcnt lgkmcnt(0)
	v_mfma_f32_16x16x32_bf16 v[116:119], v[140:143], v[156:159], v[116:119]
	ds_read_b64_tr_b16 v[120:121], v227 offset:49152
	ds_read_b64_tr_b16 v[122:123], v228 offset:49664
	ds_read_b64_tr_b16 v[124:125], v227 offset:53248
	ds_read_b64_tr_b16 v[126:127], v228 offset:53760
	ds_read_b64_tr_b16 v[136:137], v227 offset:57344
	ds_read_b64_tr_b16 v[138:139], v228 offset:57856
	v_mul_f32_e32 v50, v144, v50
	v_mul_f32_e32 v51, v145, v51
	v_mul_f32_e32 v48, v146, v48
	v_mul_f32_e32 v49, v147, v49
	ds_read_b64_tr_b16 v[140:141], v227 offset:61440
	ds_read_b64_tr_b16 v[142:143], v228 offset:61952
	ds_read_b64_tr_b16 v[156:157], v229 offset:49152
	ds_read_b64_tr_b16 v[158:159], v230 offset:49664
	ds_read_b64_tr_b16 v[194:195], v229 offset:53248
	ds_read_b64_tr_b16 v[196:197], v230 offset:53760
	ds_read_b64_tr_b16 v[224:225], v229 offset:57344
	ds_read_b64_tr_b16 v[226:227], v230 offset:57856
	ds_read_b64_tr_b16 v[234:235], v229 offset:61440
	ds_read_b64_tr_b16 v[236:237], v230 offset:61952
	s_waitcnt lgkmcnt(14)
	v_mfma_f32_16x16x32_bf16 v[48:51], v[120:123], v[72:75], v[48:51]
	v_mul_f32_e64 v54, v144, v54
	v_mul_f32_e64 v55, v145, v55
	v_mul_f32_e32 v52, v146, v52
	v_mul_f32_e32 v53, v147, v53
	v_mul_f32_e32 v58, v144, v58
	v_mul_f32_e32 v59, v145, v59
	s_waitcnt lgkmcnt(12)
	v_mfma_f32_16x16x32_bf16 v[48:51], v[124:127], v[80:83], v[48:51]
	v_mul_f32_e64 v56, v146, v56
	v_mul_f32_e64 v57, v147, v57
	v_mul_f32_e32 v62, v144, v62
	v_mul_f32_e32 v63, v145, v63
	v_mul_f32_e32 v60, v146, v60
	v_mul_f32_e32 v61, v147, v61
	s_waitcnt lgkmcnt(10)
	v_mfma_f32_16x16x32_bf16 v[48:51], v[136:139], v[88:91], v[48:51]
	s_add_u32 s12, s23, s40
	v_lshl_add_u32 v192, v192, 12, v213
	s_addc_u32 s13, s92, s41
	s_waitcnt lgkmcnt(8)
	v_mfma_f32_16x16x32_bf16 v[48:51], v[140:143], v[92:95], v[48:51]
	ds_read_b64_tr_b16 v[120:121], v231 offset:49152
	ds_read_b64_tr_b16 v[122:123], v232 offset:49664
	ds_read_b64_tr_b16 v[124:125], v231 offset:53248
	ds_read_b64_tr_b16 v[126:127], v232 offset:53760
	ds_read_b64_tr_b16 v[136:137], v231 offset:57344
	ds_read_b64_tr_b16 v[138:139], v232 offset:57856
	ds_read_b64_tr_b16 v[140:141], v231 offset:61440
	ds_read_b64_tr_b16 v[142:143], v232 offset:61952
	s_waitcnt lgkmcnt(14)
	v_mfma_f32_16x16x32_bf16 v[52:55], v[156:159], v[72:75], v[52:55]
	s_add_u32 s40, s40, 0xfff00000
	s_addc_u32 s41, s41, -1
	s_add_i32 s59, s59, 1
	s_waitcnt lgkmcnt(12)
	v_mfma_f32_16x16x32_bf16 v[52:55], v[194:197], v[80:83], v[52:55]
	s_add_i32 s38, s38, -1
	s_waitcnt lgkmcnt(10)
; #define GAS __attribute__((address_space(1)))
; __device__ __forceinline__ unsigned cvt_pk_bf16(float lo, float hi) { unsigned r; asm volatile("v_cvt_pk_bf16_f32 %0, %1, %2" : "=v"(r) : "v"(lo), "v"(hi)); return r; }
; __device__ __forceinline__ bf16x8 pack8(s16x4 lo, s16x4 hi) { return (bf16x8){lo[0], lo[1], lo[2], lo[3], hi[0], hi[1], hi[2], hi[3]}; }
; #define SCAN_BAR() asm volatile("s_waitcnt lgkmcnt(0)\n\ts_barrier" ::: "memory")
; #define SCAN_KREAD(b_, mt_) do { _Pragma("unroll") for (int ks = 0; ks < 4; ++ks) { const int ko = ((p & 1) ? LK1 : LK0) + 32 * ks * QS; kl[b_][ks] = tr_read(bKlo[mt_] + ko); kh[b_][ks] = tr_read(bKhi[mt_] + ko); } } while (0)
; __device__ __forceinline__ void scan_phase(const Frame& F, const bf16_t* Q, const bf16_t* K, const bf16_t* V, const bf16_t* PB, bf16_t* OF, bf16_t* OB, int half) {
;     ...
;                 for (int mt = 0; mt < 4; ++mt) { if (mt < 3) SCAN_KREAD((mt + 1) & 1, mt + 1);
;                     f32x4 acc = Rt[4 * p + mt] * c1;
; #pragma unroll
;                     for (int ks = 0; ks < 4; ++ks) acc = __builtin_amdgcn_mfma_f32_16x16x32_bf16(pack8(kl[mt & 1][ks], kh[mt & 1][ks]), Vf[ks], acc, 0, 0, 0);
;                     Rt[4 * p + mt] = acc; }
;     ...
;                 __builtin_amdgcn_sched_group_barrier(0x100, 8, 0);
;                 __builtin_amdgcn_sched_group_barrier(0x100, 8, 0); __builtin_amdgcn_sched_group_barrier(0x8, 4, 0);
;                 __builtin_amdgcn_sched_group_barrier(0x100, 8, 0); __builtin_amdgcn_sched_group_barrier(0x8, 4, 0);
;                 __builtin_amdgcn_sched_group_barrier(0x100, 8, 0); __builtin_amdgcn_sched_group_barrier(0x8, 4, 0);
;                 __builtin_amdgcn_sched_group_barrier(0x8, 4, 0);
;                 }
;                 if (p == 3) {
;                     bf16_t* ob_ = O + r0 * 4096 + head * 512 + vq * 128; const unsigned lo_ = (unsigned)(l15_l * 4096 + 16 * wv + 4 * quad);
;                     float fi = __builtin_amdgcn_exp2f(lg2 * (float)(dir ? 128 - l15_l : l15_l + 1));
; #pragma unroll
;                     for (int it = 0; it < 8; ++it) {
;                         *(GAS u32x2*)(ob_ + (size_t)(16 * it) * 4096 + lo_) = (u32x2){cvt_pk_bf16(Ot[it][0] * fi, Ot[it][1] * fi), cvt_pk_bf16(Ot[it][2] * fi, Ot[it][3] * fi)}; fi *= gm16; }
;                 }
;                 SCAN_BAR();
	v_mfma_f32_16x16x32_bf16 v[52:55], v[224:227], v[88:91], v[52:55]
	s_waitcnt lgkmcnt(8)
	v_mfma_f32_16x16x32_bf16 v[52:55], v[234:237], v[92:95], v[52:55]
	ds_read_b64_tr_b16 v[156:157], v233 offset:49152
	ds_read_b64_tr_b16 v[158:159], v241 offset:49664
	ds_read_b64_tr_b16 v[194:195], v233 offset:53248
	ds_read_b64_tr_b16 v[196:197], v241 offset:53760
	ds_read_b64_tr_b16 v[224:225], v233 offset:57344
	ds_read_b64_tr_b16 v[226:227], v241 offset:57856
	ds_read_b64_tr_b16 v[228:229], v233 offset:61440
	ds_read_b64_tr_b16 v[230:231], v241 offset:61952
	s_waitcnt lgkmcnt(14)
	v_mfma_f32_16x16x32_bf16 v[56:59], v[120:123], v[72:75], v[56:59]
	s_waitcnt lgkmcnt(12)
	v_mfma_f32_16x16x32_bf16 v[56:59], v[124:127], v[80:83], v[56:59]
	s_waitcnt lgkmcnt(10)
	v_mfma_f32_16x16x32_bf16 v[56:59], v[136:139], v[88:91], v[56:59]
	s_waitcnt lgkmcnt(8)
	v_mfma_f32_16x16x32_bf16 v[56:59], v[140:143], v[92:95], v[56:59]
	s_waitcnt lgkmcnt(6)
	v_mfma_f32_16x16x32_bf16 v[60:63], v[156:159], v[72:75], v[60:63]
	v_mul_f32_e32 v72, s54, v238
	s_waitcnt lgkmcnt(4)
	v_mfma_f32_16x16x32_bf16 v[60:63], v[194:197], v[80:83], v[60:63]
	v_exp_f32_e32 v82, v72
	v_lshl_add_u64 v[72:73], v[192:193], 1, s[12:13]
	s_mov_b32 s12, 0x180000
	s_waitcnt lgkmcnt(2)
	v_mfma_f32_16x16x32_bf16 v[60:63], v[224:227], v[88:91], v[60:63]
	v_mul_f32_e32 v74, v82, v128
	v_mul_f32_e32 v75, v82, v129
	v_cvt_pk_bf16_f32 v74, v74, v75
	v_mul_f32_e32 v75, v82, v130
	v_mul_f32_e32 v80, v82, v131
	v_cvt_pk_bf16_f32 v75, v75, v80
	v_add_co_u32_e32 v80, vcc, s6, v72
	v_mul_f32_e32 v82, s87, v82
	s_nop 0
	v_addc_co_u32_e32 v81, vcc, 0, v73, vcc
	global_store_dwordx2 v[80:81], v[74:75], off
	v_mul_f32_e32 v74, v82, v132
	v_mul_f32_e32 v75, v82, v133
	v_cvt_pk_bf16_f32 v74, v74, v75
	v_mul_f32_e32 v75, v82, v134
	v_mul_f32_e32 v80, v82, v135
	v_cvt_pk_bf16_f32 v75, v75, v80
	v_add_co_u32_e32 v80, vcc, s7, v72
	v_mul_f32_e32 v82, s87, v82
	s_nop 0
	v_addc_co_u32_e32 v81, vcc, 0, v73, vcc
	global_store_dwordx2 v[80:81], v[74:75], off
	v_mul_f32_e32 v74, v82, v104
	v_mul_f32_e32 v75, v82, v105
	v_cvt_pk_bf16_f32 v74, v74, v75
	v_mul_f32_e32 v75, v82, v106
	v_mul_f32_e32 v80, v82, v107
	v_cvt_pk_bf16_f32 v75, v75, v80
	v_add_co_u32_e32 v80, vcc, s4, v72
	v_mul_f32_e32 v82, s87, v82
	s_nop 0
	v_addc_co_u32_e32 v81, vcc, 0, v73, vcc
	global_store_dwordx2 v[80:81], v[74:75], off
	v_mul_f32_e32 v74, v82, v108
	v_mul_f32_e32 v75, v82, v109
	v_cvt_pk_bf16_f32 v74, v74, v75
	v_mul_f32_e32 v75, v82, v110
	v_mul_f32_e32 v80, v82, v111
	v_cvt_pk_bf16_f32 v75, v75, v80
	v_add_co_u32_e32 v80, vcc, s5, v72
	v_mul_f32_e32 v82, s87, v82
	s_nop 0
	v_addc_co_u32_e32 v81, vcc, 0, v73, vcc
	global_store_dwordx2 v[80:81], v[74:75], off
	v_mul_f32_e32 v74, v82, v112
	v_mul_f32_e32 v75, v82, v113
	v_cvt_pk_bf16_f32 v74, v74, v75
	v_mul_f32_e32 v75, v82, v114
	v_mul_f32_e32 v80, v82, v115
	v_cvt_pk_bf16_f32 v75, v75, v80
	v_add_co_u32_e32 v80, vcc, s12, v72
	v_mul_f32_e32 v82, s87, v82
	s_nop 0
	v_addc_co_u32_e32 v81, vcc, 0, v73, vcc
	global_store_dwordx2 v[80:81], v[74:75], off
	v_mul_f32_e32 v74, v82, v100
	v_mul_f32_e32 v75, v82, v101
	v_cvt_pk_bf16_f32 v74, v74, v75
	v_mul_f32_e32 v75, v82, v102
	v_mul_f32_e32 v80, v82, v103
	s_mov_b32 s12, 0x1a0000
	v_cvt_pk_bf16_f32 v75, v75, v80
	v_add_co_u32_e32 v80, vcc, s12, v72
	v_mul_f32_e32 v82, s87, v82
	s_nop 0
	v_addc_co_u32_e32 v81, vcc, 0, v73, vcc
	global_store_dwordx2 v[80:81], v[74:75], off
	v_mul_f32_e32 v74, v82, v96
	v_mul_f32_e32 v75, v82, v97
	v_cvt_pk_bf16_f32 v74, v74, v75
	v_mul_f32_e32 v75, v82, v98
	v_mul_f32_e32 v80, v82, v99
	s_mov_b32 s12, 0x1c0000
	v_cvt_pk_bf16_f32 v75, v75, v80
	v_add_co_u32_e32 v80, vcc, s12, v72
	s_mov_b32 s12, 0x1e0000
	s_nop 0
	v_addc_co_u32_e32 v81, vcc, 0, v73, vcc
	global_store_dwordx2 v[80:81], v[74:75], off
	v_mul_f32_e32 v75, s87, v82
	v_mul_f32_e32 v74, v75, v116
	v_mul_f32_e32 v80, v75, v117
	v_add_co_u32_e32 v72, vcc, s12, v72
	v_cvt_pk_bf16_f32 v74, v74, v80
	v_mul_f32_e32 v80, v75, v118
	v_mul_f32_e32 v75, v75, v119
	v_addc_co_u32_e32 v73, vcc, 0, v73, vcc
	s_waitcnt lgkmcnt(0)
	v_mfma_f32_16x16x32_bf16 v[60:63], v[228:231], v[92:95], v[60:63]
	v_cvt_pk_bf16_f32 v75, v80, v75
	global_store_dwordx2 v[72:73], v[74:75], off
	s_add_i32 s12, s48, s40
	s_add_u32 s42, s42, 0xfff80000
	s_waitcnt lgkmcnt(0)
	s_barrier
	s_addc_u32 s43, s43, -1
	s_cmp_eq_u32 s12, 0xffe00000
	s_cbranch_scc1 .LBB0_984
	.p2align 6
; #define LAS __attribute__((address_space(3)))
; __device__ __forceinline__ void scan_phase(const Frame& F, const bf16_t* Q, const bf16_t* K, const bf16_t* V, const bf16_t* PB, bf16_t* OF, bf16_t* OB, int half) {
;     ...
;         unsigned pmk[2][4];
; #pragma unroll
;         for (int par = 0; par < 2; ++par) { int nk = 16 * par + l15 - 8 * quad + 1; nk = nk < 0 ? 0 : (nk > 8 ? 8 : nk);
; #pragma unroll
;             for (int d_ = 0; d_ < 4; ++d_) { const unsigned mf = ((2 * d_ < nk) ? 0xffffu : 0u) | ((2 * d_ + 1 < nk) ? 0xffff0000u : 0u); pmk[par][d_] = dir ? ~mf : mf; } }
;         { const int c0 = dir ? nchunk - 1 : 0; SCAN_DMA_VP(c0); SCAN_LOAD_QK(c0, 0); SCAN_WRITE_QK(0); SCAN_LOAD_QK(c0, 1); }
;         SCAN_BAR();
;         for (int s = 0; s < nchunk; ++s) {
;             const int c = dir ? nchunk - 1 - s : s, cn = dir ? nchunk - 2 - s : s + 1; const size_t r0 = rb + (size_t)c * 128; const bool more = s + 1 < nchunk;
;             f32x4 Ot[8]; bf16x8 Vf[4];
; #pragma unroll
;             for (int i = 0; i < 8; ++i) Ot[i] = (f32x4){0.f, 0.f, 0.f, 0.f};
;             int quad_l = quad, l15_l = l15; asm volatile("" : "+v"(quad_l), "+v"(l15_l));
; #pragma unroll
;             for (int p = 0; p < 4; ++p) {
;                 if (p < 3 || more) SCAN_WRITE_QK((p + 1) & 1);
;                 if (p == 1 && more) SCAN_DMA_VP(cn);
;                 if (p < 2) SCAN_LOAD_QK(c, p + 2); else if (more) SCAN_LOAD_QK(cn, p - 2);
;                 if (p == 0) {
; #pragma unroll
;                     for (int ks = 0; ks < 4; ++ks) { const s16x4 lo = tr_read(bVlo + 32 * ks * 256), hi = tr_read(bVhi + 32 * ks * 256); Vf[ks] = pack8(lo, hi); }
;                     __builtin_amdgcn_sched_barrier(0);
;                     { u32x4 pwb[2];
;                       { constexpr int q0_ = pv_pair(dir, 0); pwb[0] = *(const LAS u32x4*)(bPk[q0_ & 3] + 16 * (q0_ >> 2) * 256); }
;                       __builtin_amdgcn_sched_group_barrier(0x100, 1, 0);
;                       mattn_sfor<0, 20>([&](auto n_) { constexpr int n = decltype(n_)::value, pr = pv_pair(dir, n), it = pr >> 2, ks = pr & 3, dks = ks - (it >> 1);
;                           if constexpr (n + 1 < 20) { constexpr int nx = pv_pair(dir, n + 1); pwb[(n + 1) & 1] = *(const LAS u32x4*)(bPk[nx & 3] + 16 * (nx >> 2) * 256); }
;                           u32x4 pw = pwb[n & 1];
.LBB0_978:
	v_lshl_add_u64 v[158:159], v[154:155], 0, s[42:43]
	s_mov_b32 s12, 0x10780000
	v_add_co_u32_e32 v72, vcc, s12, v158
	v_mov_b32_e32 v192, v161
	v_mov_b32_e32 v74, v162
	v_lshl_add_u64 v[156:157], v[152:153], 0, s[42:43]
	v_addc_co_u32_e32 v73, vcc, 0, v159, vcc
	s_mov_b32 s12, 0x4a880000
	global_load_dwordx4 v[96:99], v[72:73], off offset:256
	v_add_co_u32_e32 v72, vcc, s12, v156
	s_mov_b32 s12, 0x107c0000
	s_nop 0
	v_addc_co_u32_e32 v73, vcc, 0, v157, vcc
	global_load_dwordx4 v[100:103], v[72:73], off offset:256
	v_add_co_u32_e32 v72, vcc, s12, v158
	s_mov_b32 s12, 0x4a8c0000
	s_nop 0
	v_addc_co_u32_e32 v73, vcc, 0, v159, vcc
	global_load_dwordx4 v[104:107], v[72:73], off offset:256
	v_add_co_u32_e32 v72, vcc, s12, v156
	s_waitcnt vmcnt(14)
	ds_write_b128 v214, v[64:67] offset:16384
	v_addc_co_u32_e32 v73, vcc, 0, v157, vcc
	global_load_dwordx4 v[108:111], v[72:73], off offset:256
	s_waitcnt vmcnt(14)
	ds_write_b128 v214, v[68:71] offset:49152
	s_waitcnt vmcnt(13)
	ds_write_b128 v214, v[76:79] offset:24576
	s_waitcnt vmcnt(12)
	ds_write_b128 v214, v[84:87] offset:57344
	v_add_u32_e32 v64, v175, v168
	v_add_u32_e32 v65, v169, v168
	v_lshlrev_b32_e32 v112, 3, v74
	ds_read_b64_tr_b16 v[72:73], v64
	ds_read_b64_tr_b16 v[80:81], v64 offset:8192
	ds_read_b64_tr_b16 v[88:89], v64 offset:16384
	ds_read_b64_tr_b16 v[92:93], v64 offset:24576
	ds_read_b64_tr_b16 v[74:75], v65 offset:1024
	ds_read_b64_tr_b16 v[82:83], v65 offset:9216
	ds_read_b64_tr_b16 v[90:91], v65 offset:17408
	ds_read_b64_tr_b16 v[94:95], v65 offset:25600
	v_cvt_f32_i32_e32 v124, v112
	s_cmp_lt_u32 s59, s73
	s_cselect_b64 s[44:45], -1, 0
	s_cmp_ge_u32 s59, s73
	v_add_u32_e32 v84, v170, v171
	ds_read_b128 v[64:67], v84
	v_add_u32_e32 v116, v170, v172
	ds_read_b128 v[68:71], v116
	v_add_u32_e32 v120, v170, v173
	v_add_u32_e32 v125, v170, v174
	s_waitcnt lgkmcnt(1)
	v_and_b32_e32 v64, v64, v191
	v_and_b32_e32 v65, v65, v198
	v_and_b32_e32 v66, v66, v199
	v_and_b32_e32 v67, v67, v200
	s_nop 1
	v_mfma_f32_16x16x32_bf16 v[64:67], v[72:75], v[64:67], 0
	ds_read_b128 v[76:79], v120
	s_waitcnt lgkmcnt(1)
	v_mfma_f32_16x16x32_bf16 v[64:67], v[80:83], v[68:71], v[64:67]
	ds_read_b128 v[68:71], v125
	s_waitcnt lgkmcnt(1)
	v_mfma_f32_16x16x32_bf16 v[64:67], v[88:91], v[76:79], v[64:67]
	ds_read_b128 v[76:79], v84 offset:4096
	s_waitcnt lgkmcnt(0)
	v_and_b32_e32 v76, v76, v201
	v_mfma_f32_16x16x32_bf16 v[64:67], v[92:95], v[68:71], v[64:67]
	ds_read_b128 v[68:71], v116 offset:4096
	v_and_b32_e32 v77, v77, v202
	v_and_b32_e32 v78, v78, v203
	v_and_b32_e32 v79, v79, v204
	s_nop 1
	v_mfma_f32_16x16x32_bf16 v[76:79], v[72:75], v[76:79], 0
	ds_read_b128 v[84:87], v120 offset:4096
	s_waitcnt lgkmcnt(1)
	v_mfma_f32_16x16x32_bf16 v[68:71], v[80:83], v[68:71], v[76:79]
	s_nop 4
	ds_read_b128 v[76:79], v125 offset:4096
	s_waitcnt lgkmcnt(1)
	v_mfma_f32_16x16x32_bf16 v[68:71], v[88:91], v[84:87], v[68:71]
	ds_read_b128 v[84:87], v116 offset:8192
	s_waitcnt lgkmcnt(0)
	v_and_b32_e32 v84, v84, v191
	v_mfma_f32_16x16x32_bf16 v[68:71], v[92:95], v[76:79], v[68:71]
	ds_read_b128 v[76:79], v120 offset:8192
	v_and_b32_e32 v85, v85, v198
	v_and_b32_e32 v86, v86, v199
	v_and_b32_e32 v87, v87, v200
	s_nop 1
	v_mfma_f32_16x16x32_bf16 v[84:87], v[80:83], v[84:87], 0
	ds_read_b128 v[112:115], v125 offset:8192
	s_waitcnt lgkmcnt(1)
	v_mfma_f32_16x16x32_bf16 v[76:79], v[88:91], v[76:79], v[84:87]
	s_nop 4
	ds_read_b128 v[84:87], v116 offset:12288
	s_waitcnt lgkmcnt(1)
	v_mfma_f32_16x16x32_bf16 v[76:79], v[92:95], v[112:115], v[76:79]
	ds_read_b128 v[112:115], v120 offset:12288
	s_waitcnt lgkmcnt(1)
	v_and_b32_e32 v84, v84, v201
	v_and_b32_e32 v85, v85, v202
	v_and_b32_e32 v86, v86, v203
	v_and_b32_e32 v87, v87, v204
	s_nop 1
	v_mfma_f32_16x16x32_bf16 v[84:87], v[80:83], v[84:87], 0
	ds_read_b128 v[116:119], v125 offset:12288
	s_waitcnt lgkmcnt(1)
	v_mfma_f32_16x16x32_bf16 v[84:87], v[88:91], v[112:115], v[84:87]
	ds_read_b128 v[112:115], v120 offset:16384
	s_waitcnt lgkmcnt(0)
	v_and_b32_e32 v112, v112, v191
	v_and_b32_e32 v113, v113, v198
	v_and_b32_e32 v114, v114, v199
	v_and_b32_e32 v115, v115, v200
	v_mfma_f32_16x16x32_bf16 v[84:87], v[92:95], v[116:119], v[84:87]
	ds_read_b128 v[116:119], v125 offset:16384
	v_mfma_f32_16x16x32_bf16 v[112:115], v[88:91], v[112:115], 0
	ds_read_b128 v[120:123], v120 offset:20480
	s_waitcnt lgkmcnt(1)
	v_mfma_f32_16x16x32_bf16 v[128:131], v[92:95], v[116:119], v[112:115]
	s_waitcnt lgkmcnt(0)
	v_and_b32_e32 v116, v120, v201
	v_and_b32_e32 v117, v121, v202
	s_nop 1
	ds_read_b128 v[112:115], v125 offset:20480
	v_and_b32_e32 v118, v122, v203
	v_and_b32_e32 v119, v123, v204
	s_nop 1
	v_mfma_f32_16x16x32_bf16 v[116:119], v[88:91], v[116:119], 0
	ds_read_b128 v[120:123], v125 offset:24576
	s_waitcnt lgkmcnt(1)
	v_mfma_f32_16x16x32_bf16 v[132:135], v[92:95], v[112:115], v[116:119]
	ds_read_b128 v[112:115], v125 offset:28672
	s_waitcnt lgkmcnt(0)
; #define LAS __attribute__((address_space(3)))
; __device__ __forceinline__ void scan_phase(const Frame& F, const bf16_t* Q, const bf16_t* K, const bf16_t* V, const bf16_t* PB, bf16_t* OF, bf16_t* OB, int half) {
;     ...
;                       mattn_sfor<0, 20>([&](auto n_) { constexpr int n = decltype(n_)::value, pr = pv_pair(dir, n), it = pr >> 2, ks = pr & 3, dks = ks - (it >> 1);
;                           if constexpr (n + 1 < 20) { constexpr int nx = pv_pair(dir, n + 1); pwb[(n + 1) & 1] = *(const LAS u32x4*)(bPk[nx & 3] + 16 * (nx >> 2) * 256); }
;                           u32x4 pw = pwb[n & 1];
;                           if constexpr (dks == 0) { pw.x &= pmk[it & 1][0]; pw.y &= pmk[it & 1][1]; pw.z &= pmk[it & 1][2]; pw.w &= pmk[it & 1][3]; }
;                           Ot[it] = __builtin_amdgcn_mfma_f32_16x16x32_bf16(Vf[ks], __builtin_bit_cast(bf16x8, pw), Ot[it], 0, 0, 0);
;                           __builtin_amdgcn_sched_group_barrier(0x100, 1, 0); __builtin_amdgcn_sched_group_barrier(0x8, 1, 0); }); }
;                     __builtin_amdgcn_sched_barrier(0);
;                     { float fk = __builtin_amdgcn_exp2f(lg2 * (float)(dir ? 8 * quad_l : 127 - 8 * quad_l));
; #pragma unroll
;                       for (int ks = 0; ks < 4; ++ks) { u32x4 vw = __builtin_bit_cast(u32x4, Vf[ks]); float f = fk;
; #pragma unroll
;                         for (int e2 = 0; e2 < 4; ++e2) { const float f0 = f, f1 = f * gm1; f = f1 * gm1;
;                             vw[e2] = cvt_pk_bf16(bf_lo(vw[e2]) * f0, bf_hi(vw[e2]) * f1); }
;                         Vf[ks] = __builtin_bit_cast(bf16x8, vw); fk *= gm32; } }
;                 }
;                 __builtin_amdgcn_sched_barrier(0);
;                 {
;                     bf16x8 Rf[2];
; #pragma unroll
;                     for (int ks = 0; ks < 2; ++ks) { const f32x4 r0v = Rt[4 * p + 2 * ks], r1v = Rt[4 * p + 2 * ks + 1];
;                         const u32x4 wvv = {cvt_pk_bf16(r0v[0], r0v[1]), cvt_pk_bf16(r0v[2], r0v[3]), cvt_pk_bf16(r1v[0], r1v[1]), cvt_pk_bf16(r1v[2], r1v[3])};
;                         Rf[ks] = __builtin_bit_cast(bf16x8, wvv); }
;                     u32x4 qf[2][2];
;     ...
;                     SCAN_QREAD(0, 0);
; #pragma unroll
;                     for (int it = 0; it < 8; ++it) { if (it < 7) SCAN_QREAD((it + 1) & 1, it + 1);
; #pragma unroll
	v_and_b32_e32 v112, v112, v201
	s_nop 1
	v_and_b32_e32 v116, v120, v191
	v_and_b32_e32 v117, v121, v198
	v_and_b32_e32 v118, v122, v199
	v_and_b32_e32 v119, v123, v200
	v_and_b32_e32 v113, v113, v202
	v_and_b32_e32 v114, v114, v203
	v_and_b32_e32 v115, v115, v204
	v_mfma_f32_16x16x32_bf16 v[136:139], v[92:95], v[116:119], 0
	s_nop 0
	v_mfma_f32_16x16x32_bf16 v[140:143], v[92:95], v[112:115], 0
	v_mul_f32_e32 v112, s54, v124
	v_exp_f32_e32 v112, v112
	v_lshlrev_b32_e32 v113, 16, v72
	v_and_b32_e32 v72, 0xffff0000, v72
	v_lshlrev_b32_e32 v116, 16, v73
	v_mul_f32_e32 v114, s85, v112
	v_mul_f32_e32 v113, v112, v113
	v_mul_f32_e32 v115, s85, v114
	v_mul_f32_e32 v72, v114, v72
	v_cvt_pk_bf16_f32 v72, v113, v72
	v_mul_f32_e32 v113, s85, v115
	v_mul_f32_e32 v114, s85, v113
	v_and_b32_e32 v73, 0xffff0000, v73
	v_mul_f32_e32 v115, v115, v116
	v_mul_f32_e32 v73, v113, v73
	v_mul_f32_e32 v113, s85, v114
	v_lshlrev_b32_e32 v116, 16, v74
	v_and_b32_e32 v74, 0xffff0000, v74
	v_cvt_pk_bf16_f32 v73, v115, v73
	v_mul_f32_e32 v115, s85, v113
	v_mul_f32_e32 v114, v114, v116
	v_mul_f32_e32 v74, v113, v74
	v_cvt_pk_bf16_f32 v74, v114, v74
	v_mul_f32_e32 v113, s85, v115
	v_lshlrev_b32_e32 v114, 16, v75
	v_and_b32_e32 v75, 0xffff0000, v75
	v_mul_f32_e32 v112, s86, v112
	v_mul_f32_e32 v114, v115, v114
	v_mul_f32_e32 v75, v113, v75
	v_mul_f32_e32 v113, s85, v112
	v_cvt_pk_bf16_f32 v75, v114, v75
	v_mul_f32_e32 v114, s85, v113
	v_lshlrev_b32_e32 v115, 16, v80
	v_and_b32_e32 v80, 0xffff0000, v80
	v_mul_f32_e32 v115, v112, v115
	v_mul_f32_e32 v80, v113, v80
	v_mul_f32_e32 v113, s85, v114
	v_cvt_pk_bf16_f32 v80, v115, v80
	v_mul_f32_e32 v115, s85, v113
	v_lshlrev_b32_e32 v116, 16, v81
	v_and_b32_e32 v81, 0xffff0000, v81
	v_mul_f32_e32 v114, v114, v116
	v_mul_f32_e32 v81, v113, v81
	v_mul_f32_e32 v113, s85, v115
	v_lshlrev_b32_e32 v116, 16, v82
	v_and_b32_e32 v82, 0xffff0000, v82
	v_cvt_pk_bf16_f32 v81, v114, v81
	v_mul_f32_e32 v114, s85, v113
	v_mul_f32_e32 v115, v115, v116
	v_mul_f32_e32 v82, v113, v82
	v_cvt_pk_bf16_f32 v82, v115, v82
	v_mul_f32_e32 v113, s85, v114
	v_lshlrev_b32_e32 v115, 16, v83
	v_and_b32_e32 v83, 0xffff0000, v83
	v_mul_f32_e32 v112, s86, v112
	v_mul_f32_e32 v114, v114, v115
	v_mul_f32_e32 v83, v113, v83
	v_mul_f32_e32 v113, s85, v112
	v_cvt_pk_bf16_f32 v83, v114, v83
	v_mul_f32_e32 v114, s85, v113
	v_lshlrev_b32_e32 v115, 16, v88
	v_and_b32_e32 v88, 0xffff0000, v88
	v_mul_f32_e32 v115, v112, v115
	v_mul_f32_e32 v88, v113, v88
	v_mul_f32_e32 v113, s85, v114
	v_cvt_pk_bf16_f32 v88, v115, v88
	v_mul_f32_e32 v115, s85, v113
	v_lshlrev_b32_e32 v116, 16, v89
	v_and_b32_e32 v89, 0xffff0000, v89
	v_mul_f32_e32 v114, v114, v116
	v_mul_f32_e32 v89, v113, v89
	v_mul_f32_e32 v113, s85, v115
	v_lshlrev_b32_e32 v116, 16, v90
	v_and_b32_e32 v90, 0xffff0000, v90
	v_cvt_pk_bf16_f32 v89, v114, v89
	v_mul_f32_e32 v114, s85, v113
	v_mul_f32_e32 v115, v115, v116
	v_mul_f32_e32 v90, v113, v90
	v_cvt_pk_bf16_f32 v90, v115, v90
	v_mul_f32_e32 v113, s85, v114
	v_lshlrev_b32_e32 v115, 16, v91
	v_and_b32_e32 v91, 0xffff0000, v91
	v_mul_f32_e32 v112, s86, v112
	v_mul_f32_e32 v114, v114, v115
	v_mul_f32_e32 v91, v113, v91
	v_mul_f32_e32 v113, s85, v112
	v_lshlrev_b32_e32 v115, 16, v92
	v_and_b32_e32 v92, 0xffff0000, v92
	v_cvt_pk_bf16_f32 v91, v114, v91
	v_mul_f32_e32 v114, s85, v113
	v_mul_f32_e32 v112, v112, v115
	v_mul_f32_e32 v92, v113, v92
	v_cvt_pk_bf16_f32 v92, v112, v92
	v_mul_f32_e32 v112, s85, v114
	v_mul_f32_e32 v113, s85, v112
	v_lshlrev_b32_e32 v115, 16, v93
	v_and_b32_e32 v93, 0xffff0000, v93
	v_mul_f32_e32 v114, v114, v115
	v_mul_f32_e32 v93, v112, v93
	v_mul_f32_e32 v112, s85, v113
	v_lshlrev_b32_e32 v115, 16, v94
	v_and_b32_e32 v94, 0xffff0000, v94
	v_cvt_pk_bf16_f32 v93, v114, v93
	v_mul_f32_e32 v114, s85, v112
	v_mul_f32_e32 v113, v113, v115
	v_mul_f32_e32 v94, v112, v94
	v_cvt_pk_bf16_f32 v94, v113, v94
	v_mul_f32_e32 v112, s85, v114
	v_lshlrev_b32_e32 v113, 16, v95
	v_and_b32_e32 v95, 0xffff0000, v95
	v_mul_f32_e32 v113, v114, v113
	v_mul_f32_e32 v95, v112, v95
	v_cvt_pk_bf16_f32 v95, v113, v95
	v_add_u32_e32 v223, v163, v164
	v_add_u32_e32 v224, v163, v165
	v_cvt_pk_bf16_f32 v228, v44, v45
	v_cvt_pk_bf16_f32 v229, v46, v47
	v_cvt_pk_bf16_f32 v230, v40, v41
	v_cvt_pk_bf16_f32 v231, v42, v43
	v_cvt_pk_bf16_f32 v242, v36, v37
	v_cvt_pk_bf16_f32 v243, v38, v39
	v_cvt_pk_bf16_f32 v244, v32, v33
	v_cvt_pk_bf16_f32 v245, v34, v35
	ds_read_b64 v[112:113], v223
	ds_read_b64 v[114:115], v224
	v_add_u32_e32 v225, v163, v166
	v_add_u32_e32 v226, v163, v167
	ds_read_b64 v[116:117], v225
	ds_read_b64 v[118:119], v226
	ds_read_b64 v[120:121], v223 offset:2048
	ds_read_b64 v[122:123], v224 offset:2048
	ds_read_b64 v[124:125], v225 offset:2048
	ds_read_b64 v[126:127], v226 offset:2048
	s_waitcnt lgkmcnt(6)
	v_mfma_f32_16x16x32_bf16 v[64:67], v[228:231], v[112:115], v[64:67]
	s_waitcnt lgkmcnt(4)
	v_mfma_f32_16x16x32_bf16 v[112:115], v[242:245], v[116:119], v[64:67]
	s_nop 5
	ds_read_b64 v[64:65], v223 offset:4096
	ds_read_b64 v[66:67], v224 offset:4096
	ds_read_b64 v[246:247], v225 offset:4096
	ds_read_b64 v[248:249], v226 offset:4096
	s_waitcnt lgkmcnt(6)
	v_mfma_f32_16x16x32_bf16 v[68:71], v[228:231], v[120:123], v[68:71]
	s_waitcnt lgkmcnt(4)
	v_mfma_f32_16x16x32_bf16 v[116:119], v[242:245], v[124:127], v[68:71]
	s_nop 5
	ds_read_b64 v[68:69], v223 offset:6144
	ds_read_b64 v[70:71], v224 offset:6144
	ds_read_b64 v[124:125], v225 offset:6144
	ds_read_b64 v[126:127], v226 offset:6144
	s_waitcnt lgkmcnt(6)
	v_mfma_f32_16x16x32_bf16 v[64:67], v[228:231], v[64:67], v[76:79]
	s_waitcnt lgkmcnt(4)
; __device__ __forceinline__ bf16x8 pack8(s16x4 lo, s16x4 hi) { return (bf16x8){lo[0], lo[1], lo[2], lo[3], hi[0], hi[1], hi[2], hi[3]}; }
; __device__ __forceinline__ void scan_phase(const Frame& F, const bf16_t* Q, const bf16_t* K, const bf16_t* V, const bf16_t* PB, bf16_t* OF, bf16_t* OB, int half) {
;     ...
;         unsigned pmk[2][4];
; #pragma unroll
;         for (int par = 0; par < 2; ++par) { int nk = 16 * par + l15 - 8 * quad + 1; nk = nk < 0 ? 0 : (nk > 8 ? 8 : nk);
; #pragma unroll
;     ...
;                     SCAN_QREAD(0, 0);
; #pragma unroll
;                     for (int it = 0; it < 8; ++it) { if (it < 7) SCAN_QREAD((it + 1) & 1, it + 1);
; #pragma unroll
;                         for (int ks = 0; ks < 2; ++ks) Ot[it] = __builtin_amdgcn_mfma_f32_16x16x32_bf16(Rf[ks], __builtin_bit_cast(bf16x8, qf[it & 1][ks]), Ot[it], 0, 0, 0); }
;     ...
;                     __builtin_amdgcn_sched_group_barrier(0x100, 4, 0);
;                     __builtin_amdgcn_sched_group_barrier(0x100, 4, 0); __builtin_amdgcn_sched_group_barrier(0x8, 2, 0);
;                     __builtin_amdgcn_sched_group_barrier(0x100, 4, 0); __builtin_amdgcn_sched_group_barrier(0x8, 2, 0);
;                     __builtin_amdgcn_sched_group_barrier(0x100, 4, 0); __builtin_amdgcn_sched_group_barrier(0x8, 2, 0);
;                     __builtin_amdgcn_sched_group_barrier(0x100, 4, 0); __builtin_amdgcn_sched_group_barrier(0x8, 2, 0);
;                     __builtin_amdgcn_sched_group_barrier(0x100, 4, 0); __builtin_amdgcn_sched_group_barrier(0x8, 2, 0);
;                     __builtin_amdgcn_sched_group_barrier(0x100, 4, 0); __builtin_amdgcn_sched_group_barrier(0x8, 2, 0);
;                     __builtin_amdgcn_sched_group_barrier(0x100, 4, 0); __builtin_amdgcn_sched_group_barrier(0x8, 2, 0);
;                     __builtin_amdgcn_sched_group_barrier(0x8, 2, 0);
;                 }
;                 __builtin_amdgcn_sched_barrier(0);
;                 { s16x4 kl[2][4], kh[2][4];
;     ...
;                 SCAN_KREAD(0, 0);
; #pragma unroll
;                 for (int mt = 0; mt < 4; ++mt) { if (mt < 3) SCAN_KREAD((mt + 1) & 1, mt + 1);
;                     f32x4 acc = Rt[4 * p + mt] * c1;
; #pragma unroll
;                     for (int ks = 0; ks < 4; ++ks) acc = __builtin_amdgcn_mfma_f32_16x16x32_bf16(pack8(kl[mt & 1][ks], kh[mt & 1][ks]), Vf[ks], acc, 0, 0, 0);
;                     Rt[4 * p + mt] = acc; }
	v_mfma_f32_16x16x32_bf16 v[120:123], v[242:245], v[246:249], v[64:67]
	s_nop 5
	ds_read_b64 v[64:65], v223 offset:8192
	ds_read_b64 v[66:67], v224 offset:8192
	ds_read_b64 v[76:77], v225 offset:8192
	ds_read_b64 v[78:79], v226 offset:8192
	s_waitcnt lgkmcnt(6)
	v_mfma_f32_16x16x32_bf16 v[68:71], v[228:231], v[68:71], v[84:87]
	s_waitcnt lgkmcnt(4)
	v_mfma_f32_16x16x32_bf16 v[124:127], v[242:245], v[124:127], v[68:71]
	s_nop 5
	ds_read_b64 v[68:69], v223 offset:10240
	ds_read_b64 v[70:71], v224 offset:10240
	ds_read_b64 v[84:85], v225 offset:10240
	ds_read_b64 v[86:87], v226 offset:10240
	s_waitcnt lgkmcnt(6)
	v_mfma_f32_16x16x32_bf16 v[64:67], v[228:231], v[64:67], v[128:131]
	s_waitcnt lgkmcnt(4)
	v_mfma_f32_16x16x32_bf16 v[128:131], v[242:245], v[76:79], v[64:67]
	s_nop 5
	ds_read_b64 v[64:65], v223 offset:12288
	ds_read_b64 v[66:67], v224 offset:12288
	ds_read_b64 v[76:77], v225 offset:12288
	ds_read_b64 v[78:79], v226 offset:12288
	s_waitcnt lgkmcnt(6)
	v_mfma_f32_16x16x32_bf16 v[68:71], v[228:231], v[68:71], v[132:135]
	s_waitcnt lgkmcnt(4)
	v_mfma_f32_16x16x32_bf16 v[132:135], v[242:245], v[84:87], v[68:71]
	s_nop 5
	ds_read_b64 v[68:69], v223 offset:14336
	ds_read_b64 v[70:71], v224 offset:14336
	ds_read_b64 v[84:85], v225 offset:14336
	ds_read_b64 v[86:87], v226 offset:14336
	s_waitcnt lgkmcnt(6)
	v_mfma_f32_16x16x32_bf16 v[64:67], v[228:231], v[64:67], v[136:139]
	s_waitcnt lgkmcnt(4)
	v_mfma_f32_16x16x32_bf16 v[136:139], v[242:245], v[76:79], v[64:67]
	s_waitcnt lgkmcnt(2)
	v_mfma_f32_16x16x32_bf16 v[64:67], v[228:231], v[68:71], v[140:143]
	s_waitcnt lgkmcnt(0)
	v_mfma_f32_16x16x32_bf16 v[140:143], v[242:245], v[84:87], v[64:67]
	v_add_u32_e32 v227, v182, v189
	v_add_u32_e32 v228, v182, v190
	s_nop 3
	ds_read_b64_tr_b16 v[64:65], v227 offset:32768
	ds_read_b64_tr_b16 v[66:67], v228 offset:33280
	ds_read_b64_tr_b16 v[68:69], v227 offset:36864
	ds_read_b64_tr_b16 v[70:71], v228 offset:37376
	v_mov_b32_e32 v145, v144
	ds_read_b64_tr_b16 v[76:77], v227 offset:40960
	ds_read_b64_tr_b16 v[78:79], v228 offset:41472
	v_add_u32_e32 v229, v182, v187
	v_add_u32_e32 v230, v182, v188
	v_mul_f32_e32 v46, v144, v46
	v_mul_f32_e32 v47, v145, v47
	v_mul_f32_e32 v44, v146, v44
	v_mul_f32_e32 v45, v147, v45
	ds_read_b64_tr_b16 v[84:85], v227 offset:45056
	ds_read_b64_tr_b16 v[86:87], v228 offset:45568
	ds_read_b64_tr_b16 v[242:243], v229 offset:32768
	ds_read_b64_tr_b16 v[244:245], v230 offset:33280
	ds_read_b64_tr_b16 v[246:247], v229 offset:36864
	ds_read_b64_tr_b16 v[248:249], v230 offset:37376
	ds_read_b64_tr_b16 v[194:195], v229 offset:40960
	ds_read_b64_tr_b16 v[196:197], v230 offset:41472
	ds_read_b64_tr_b16 v[238:239], v229 offset:45056
	ds_read_b64_tr_b16 v[240:241], v230 offset:45568
	s_waitcnt lgkmcnt(14)
	v_mfma_f32_16x16x32_bf16 v[44:47], v[64:67], v[72:75], v[44:47]
	v_add_u32_e32 v231, v182, v185
	v_add_u32_e32 v232, v182, v186
	v_mul_f32_e32 v42, v144, v42
	v_mul_f32_e32 v43, v145, v43
	s_waitcnt lgkmcnt(12)
	v_mfma_f32_16x16x32_bf16 v[44:47], v[68:71], v[80:83], v[44:47]
	v_mul_f32_e64 v40, v146, v40
	v_mul_f32_e64 v41, v147, v41
	v_add_u32_e32 v233, v182, v183
	v_mul_f32_e32 v38, v144, v38
	v_mul_f32_e32 v39, v145, v39
	s_waitcnt lgkmcnt(10)
	v_mfma_f32_16x16x32_bf16 v[44:47], v[76:79], v[88:91], v[44:47]
	v_mul_f32_e64 v36, v146, v36
	v_mul_f32_e64 v37, v147, v37
	v_mul_f32_e32 v34, v144, v34
	v_mul_f32_e32 v35, v145, v35
	v_mul_f32_e32 v32, v146, v32
	v_mul_f32_e32 v33, v147, v33
	s_waitcnt lgkmcnt(8)
	v_mfma_f32_16x16x32_bf16 v[44:47], v[84:87], v[92:95], v[44:47]
	ds_read_b64_tr_b16 v[64:65], v231 offset:32768
	ds_read_b64_tr_b16 v[66:67], v232 offset:33280
	ds_read_b64_tr_b16 v[68:69], v231 offset:36864
	ds_read_b64_tr_b16 v[70:71], v232 offset:37376
	ds_read_b64_tr_b16 v[76:77], v231 offset:40960
	ds_read_b64_tr_b16 v[78:79], v232 offset:41472
	ds_read_b64_tr_b16 v[84:85], v231 offset:45056
	ds_read_b64_tr_b16 v[86:87], v232 offset:45568
	s_waitcnt lgkmcnt(14)
	v_mfma_f32_16x16x32_bf16 v[40:43], v[242:245], v[72:75], v[40:43]
	s_waitcnt lgkmcnt(12)
	v_mfma_f32_16x16x32_bf16 v[40:43], v[246:249], v[80:83], v[40:43]
	s_waitcnt lgkmcnt(10)
	v_mfma_f32_16x16x32_bf16 v[40:43], v[194:197], v[88:91], v[40:43]
	s_waitcnt lgkmcnt(8)
	v_mfma_f32_16x16x32_bf16 v[40:43], v[238:241], v[92:95], v[40:43]
	v_add_u32_e32 v241, v182, v184
	ds_read_b64_tr_b16 v[194:195], v233 offset:32768
	ds_read_b64_tr_b16 v[196:197], v241 offset:33280
	ds_read_b64_tr_b16 v[242:243], v233 offset:36864
	ds_read_b64_tr_b16 v[244:245], v241 offset:37376
	ds_read_b64_tr_b16 v[246:247], v233 offset:40960
	ds_read_b64_tr_b16 v[248:249], v241 offset:41472
	ds_read_b64_tr_b16 v[234:235], v233 offset:45056
	ds_read_b64_tr_b16 v[236:237], v241 offset:45568
	s_waitcnt lgkmcnt(14)
	v_mfma_f32_16x16x32_bf16 v[36:39], v[64:67], v[72:75], v[36:39]
	s_waitcnt lgkmcnt(0)
	s_barrier
	s_waitcnt vmcnt(3)
	ds_write_b128 v214, v[96:99]
	s_waitcnt vmcnt(2)
	ds_write_b128 v214, v[100:103] offset:32768
	s_waitcnt lgkmcnt(14)
	v_mfma_f32_16x16x32_bf16 v[36:39], v[68:71], v[80:83], v[36:39]
	s_waitcnt vmcnt(1)
	ds_write_b128 v214, v[104:107] offset:8192
	s_waitcnt vmcnt(0)
	ds_write_b128 v214, v[108:111] offset:40960
	s_waitcnt lgkmcnt(14)
	v_mfma_f32_16x16x32_bf16 v[36:39], v[76:79], v[88:91], v[36:39]
	s_waitcnt lgkmcnt(12)
	v_mfma_f32_16x16x32_bf16 v[36:39], v[84:87], v[92:95], v[36:39]
	s_waitcnt lgkmcnt(10)
	v_mfma_f32_16x16x32_bf16 v[32:35], v[194:197], v[72:75], v[32:35]
	s_waitcnt lgkmcnt(8)
	v_mfma_f32_16x16x32_bf16 v[32:35], v[242:245], v[80:83], v[32:35]
	s_waitcnt lgkmcnt(6)
	v_mfma_f32_16x16x32_bf16 v[32:35], v[246:249], v[88:91], v[32:35]
	s_waitcnt lgkmcnt(4)
	v_mfma_f32_16x16x32_bf16 v[32:35], v[234:237], v[92:95], v[32:35]
	v_add_co_u32_e32 v64, vcc, 0x10780000, v158
	s_nop 1
	v_addc_co_u32_e32 v65, vcc, 0, v159, vcc
	v_add_co_u32_e32 v68, vcc, 0x4a880000, v156
	global_load_dwordx4 v[64:67], v[64:65], off offset:384
	s_nop 0
	v_addc_co_u32_e32 v69, vcc, 0, v157, vcc
	v_add_co_u32_e32 v76, vcc, 0x107c0000, v158
	global_load_dwordx4 v[68:71], v[68:69], off offset:384
	s_nop 0
	v_addc_co_u32_e32 v77, vcc, 0, v159, vcc
	v_add_co_u32_e32 v84, vcc, 0x4a8c0000, v156
	global_load_dwordx4 v[76:79], v[76:77], off offset:384
	s_nop 0
	v_addc_co_u32_e32 v85, vcc, 0, v157, vcc
	global_load_dwordx4 v[84:87], v[84:85], off offset:384
	s_cbranch_scc1 .LBB0_980
; __device__ __forceinline__ void glds16u(const void* sbase, unsigned voff, unsigned lds_dst) { unsigned keep;
;     asm volatile("s_mov_b32 %0, m0\n\ts_mov_b32 m0, %3\n\ts_nop 0\n\tglobal_load_lds_dwordx4 %1, %2\n\ts_mov_b32 m0, %0" : "=&s"(keep) : "v"(voff), "s"(sbase), "s"(lds_dst) : "memory"); }
	s_add_u32 s12, s90, s40
	s_addc_u32 s13, s91, s41
	s_ashr_i32 s39, s38, 31
	s_lshl_b64 s[34:35], s[38:39], 18
	s_add_u32 s34, s88, s34
	s_mov_b32 s39, m0
	s_mov_b32 m0, s74
	s_nop 0
	global_load_lds_dwordx4 v215, s[12:13]
	s_mov_b32 m0, s39
	s_addc_u32 s35, s89, s35
	s_mov_b32 s39, m0
	s_mov_b32 m0, s75
	s_nop 0
	global_load_lds_dwordx4 v216, s[34:35]
	s_mov_b32 m0, s39
	s_nop 0
	s_mov_b32 s39, m0
	s_mov_b32 m0, s79
	s_nop 0
	global_load_lds_dwordx4 v217, s[12:13]
	s_mov_b32 m0, s39
	s_nop 0
	s_mov_b32 s39, m0
	s_mov_b32 m0, s80
	s_nop 0
	global_load_lds_dwordx4 v218, s[34:35]
	s_mov_b32 m0, s39
	s_nop 0
	s_mov_b32 s39, m0
	s_mov_b32 m0, s81
	s_nop 0
	global_load_lds_dwordx4 v219, s[12:13]
	s_mov_b32 m0, s39
	s_nop 0
	s_mov_b32 s39, m0
	s_mov_b32 m0, s82
	s_nop 0
	global_load_lds_dwordx4 v220, s[34:35]
	s_mov_b32 m0, s39
	s_nop 0
	s_mov_b32 s39, m0
	s_mov_b32 m0, s83
	s_nop 0
	global_load_lds_dwordx4 v221, s[12:13]
	s_mov_b32 m0, s39
	s_mov_b32 s12, m0
	s_mov_b32 m0, s84
	s_nop 0
	global_load_lds_dwordx4 v222, s[34:35]
	s_mov_b32 m0, s12
; __device__ __forceinline__ void scan_phase(const Frame& F, const bf16_t* Q, const bf16_t* K, const bf16_t* V, const bf16_t* PB, bf16_t* OF, bf16_t* OB, int half) {
;     ...
;                 {
;                     bf16x8 Rf[2];
; #pragma unroll
;                     for (int ks = 0; ks < 2; ++ks) { const f32x4 r0v = Rt[4 * p + 2 * ks], r1v = Rt[4 * p + 2 * ks + 1];
;                         const u32x4 wvv = {cvt_pk_bf16(r0v[0], r0v[1]), cvt_pk_bf16(r0v[2], r0v[3]), cvt_pk_bf16(r1v[0], r1v[1]), cvt_pk_bf16(r1v[2], r1v[3])};
;                         Rf[ks] = __builtin_bit_cast(bf16x8, wvv); }
;                     u32x4 qf[2][2];
;     ...
;                     SCAN_QREAD(0, 0);
; #pragma unroll
;                     for (int it = 0; it < 8; ++it) { if (it < 7) SCAN_QREAD((it + 1) & 1, it + 1);
; #pragma unroll
;                         for (int ks = 0; ks < 2; ++ks) Ot[it] = __builtin_amdgcn_mfma_f32_16x16x32_bf16(Rf[ks], __builtin_bit_cast(bf16x8, qf[it & 1][ks]), Ot[it], 0, 0, 0); }
;     ...
;                     __builtin_amdgcn_sched_group_barrier(0x100, 4, 0);
;                     __builtin_amdgcn_sched_group_barrier(0x100, 4, 0); __builtin_amdgcn_sched_group_barrier(0x8, 2, 0);
;                     __builtin_amdgcn_sched_group_barrier(0x100, 4, 0); __builtin_amdgcn_sched_group_barrier(0x8, 2, 0);
;                     __builtin_amdgcn_sched_group_barrier(0x100, 4, 0); __builtin_amdgcn_sched_group_barrier(0x8, 2, 0);
;                     __builtin_amdgcn_sched_group_barrier(0x100, 4, 0); __builtin_amdgcn_sched_group_barrier(0x8, 2, 0);
;                     __builtin_amdgcn_sched_group_barrier(0x100, 4, 0); __builtin_amdgcn_sched_group_barrier(0x8, 2, 0);
;                     __builtin_amdgcn_sched_group_barrier(0x100, 4, 0); __builtin_amdgcn_sched_group_barrier(0x8, 2, 0);
;                     __builtin_amdgcn_sched_group_barrier(0x100, 4, 0); __builtin_amdgcn_sched_group_barrier(0x8, 2, 0);
;                     __builtin_amdgcn_sched_group_barrier(0x8, 2, 0);
;                 }
;                 __builtin_amdgcn_sched_barrier(0);
;                 { s16x4 kl[2][4], kh[2][4];
;     ...
;                 SCAN_KREAD(0, 0);
; #pragma unroll
;                 for (int mt = 0; mt < 4; ++mt) { if (mt < 3) SCAN_KREAD((mt + 1) & 1, mt + 1);
;                     f32x4 acc = Rt[4 * p + mt] * c1;
; #pragma unroll
.LBB0_980:
	v_cvt_pk_bf16_f32 v156, v28, v29
	v_cvt_pk_bf16_f32 v157, v30, v31
	v_cvt_pk_bf16_f32 v158, v20, v21
	v_cvt_pk_bf16_f32 v159, v22, v23
	v_cvt_pk_bf16_f32 v194, v16, v17
	v_cvt_pk_bf16_f32 v195, v18, v19
	v_cvt_pk_bf16_f32 v196, v24, v25
	v_cvt_pk_bf16_f32 v197, v26, v27
	ds_read_b64 v[96:97], v223 offset:16384
	ds_read_b64 v[98:99], v224 offset:16384
	ds_read_b64 v[100:101], v225 offset:16384
	ds_read_b64 v[102:103], v226 offset:16384
	ds_read_b64 v[104:105], v223 offset:18432
	ds_read_b64 v[106:107], v224 offset:18432
	ds_read_b64 v[108:109], v225 offset:18432
	ds_read_b64 v[110:111], v226 offset:18432
	s_waitcnt lgkmcnt(6)
	v_mfma_f32_16x16x32_bf16 v[96:99], v[156:159], v[96:99], v[112:115]
	s_waitcnt lgkmcnt(4)
	v_mfma_f32_16x16x32_bf16 v[96:99], v[194:197], v[100:103], v[96:99]
	s_nop 0
	ds_read_b64 v[112:113], v223 offset:20480
	ds_read_b64 v[114:115], v224 offset:20480
	ds_read_b64 v[234:235], v225 offset:20480
	ds_read_b64 v[236:237], v226 offset:20480
	s_waitcnt lgkmcnt(6)
	v_mfma_f32_16x16x32_bf16 v[100:103], v[156:159], v[104:107], v[116:119]
	s_waitcnt lgkmcnt(4)
	v_mfma_f32_16x16x32_bf16 v[100:103], v[194:197], v[108:111], v[100:103]
	ds_read_b64 v[108:109], v223 offset:22528
	ds_read_b64 v[110:111], v224 offset:22528
	ds_read_b64 v[116:117], v225 offset:22528
	ds_read_b64 v[118:119], v226 offset:22528
	s_waitcnt lgkmcnt(6)
	v_mfma_f32_16x16x32_bf16 v[104:107], v[156:159], v[112:115], v[120:123]
	s_waitcnt lgkmcnt(4)
	v_mfma_f32_16x16x32_bf16 v[104:107], v[194:197], v[234:237], v[104:107]
	ds_read_b64 v[112:113], v223 offset:24576
	ds_read_b64 v[114:115], v224 offset:24576
	ds_read_b64 v[120:121], v225 offset:24576
	ds_read_b64 v[122:123], v226 offset:24576
	s_waitcnt lgkmcnt(6)
	v_mfma_f32_16x16x32_bf16 v[108:111], v[156:159], v[108:111], v[124:127]
	s_waitcnt lgkmcnt(4)
	v_mfma_f32_16x16x32_bf16 v[108:111], v[194:197], v[116:119], v[108:111]
	ds_read_b64 v[116:117], v223 offset:26624
	ds_read_b64 v[118:119], v224 offset:26624
	ds_read_b64 v[124:125], v225 offset:26624
	ds_read_b64 v[126:127], v226 offset:26624
	s_waitcnt lgkmcnt(6)
	v_mfma_f32_16x16x32_bf16 v[112:115], v[156:159], v[112:115], v[128:131]
	s_waitcnt lgkmcnt(4)
	v_mfma_f32_16x16x32_bf16 v[112:115], v[194:197], v[120:123], v[112:115]
	ds_read_b64 v[120:121], v223 offset:28672
	ds_read_b64 v[122:123], v224 offset:28672
	ds_read_b64 v[128:129], v225 offset:28672
	ds_read_b64 v[130:131], v226 offset:28672
	s_waitcnt lgkmcnt(6)
	v_mfma_f32_16x16x32_bf16 v[116:119], v[156:159], v[116:119], v[132:135]
	s_waitcnt lgkmcnt(4)
	v_mfma_f32_16x16x32_bf16 v[116:119], v[194:197], v[124:127], v[116:119]
	ds_read_b64 v[124:125], v223 offset:30720
	ds_read_b64 v[126:127], v224 offset:30720
	ds_read_b64 v[132:133], v225 offset:30720
	ds_read_b64 v[134:135], v226 offset:30720
	s_waitcnt lgkmcnt(6)
	v_mfma_f32_16x16x32_bf16 v[120:123], v[156:159], v[120:123], v[136:139]
	s_waitcnt lgkmcnt(4)
	v_mfma_f32_16x16x32_bf16 v[120:123], v[194:197], v[128:131], v[120:123]
	s_waitcnt lgkmcnt(2)
	v_mfma_f32_16x16x32_bf16 v[124:127], v[156:159], v[124:127], v[140:143]
	s_waitcnt lgkmcnt(0)
	v_mfma_f32_16x16x32_bf16 v[124:127], v[194:197], v[132:135], v[124:127]
	ds_read_b64_tr_b16 v[128:129], v227 offset:49152
	ds_read_b64_tr_b16 v[130:131], v228 offset:49664
	ds_read_b64_tr_b16 v[132:133], v227 offset:53248
	ds_read_b64_tr_b16 v[134:135], v228 offset:53760
	ds_read_b64_tr_b16 v[136:137], v227 offset:57344
	ds_read_b64_tr_b16 v[138:139], v228 offset:57856
	v_mul_f32_e32 v30, v144, v30
	v_mul_f32_e32 v31, v145, v31
	v_mul_f32_e32 v28, v146, v28
	v_mul_f32_e32 v29, v147, v29
	ds_read_b64_tr_b16 v[140:141], v227 offset:61440
	ds_read_b64_tr_b16 v[142:143], v228 offset:61952
	ds_read_b64_tr_b16 v[156:157], v229 offset:49152
	ds_read_b64_tr_b16 v[158:159], v230 offset:49664
	ds_read_b64_tr_b16 v[194:195], v229 offset:53248
	ds_read_b64_tr_b16 v[196:197], v230 offset:53760
	ds_read_b64_tr_b16 v[234:235], v229 offset:57344
	ds_read_b64_tr_b16 v[236:237], v230 offset:57856
	ds_read_b64_tr_b16 v[242:243], v229 offset:61440
	ds_read_b64_tr_b16 v[244:245], v230 offset:61952
	s_waitcnt lgkmcnt(14)
	v_mfma_f32_16x16x32_bf16 v[28:31], v[128:131], v[72:75], v[28:31]
	v_mul_f32_e64 v22, v144, v22
	v_mul_f32_e64 v23, v145, v23
	v_mul_f32_e32 v20, v146, v20
	v_mul_f32_e32 v21, v147, v21
	v_mul_f32_e32 v18, v144, v18
	v_mul_f32_e32 v19, v145, v19
	s_waitcnt lgkmcnt(12)
	v_mfma_f32_16x16x32_bf16 v[28:31], v[132:135], v[80:83], v[28:31]
	v_mul_f32_e64 v16, v146, v16
	v_mul_f32_e64 v17, v147, v17
	v_mul_f32_e32 v26, v144, v26
	v_mul_f32_e32 v27, v145, v27
	v_mul_f32_e32 v24, v146, v24
	v_mul_f32_e32 v25, v147, v25
	s_waitcnt lgkmcnt(10)
	v_mfma_f32_16x16x32_bf16 v[28:31], v[136:139], v[88:91], v[28:31]
	s_andn2_b64 vcc, exec, s[44:45]
	s_waitcnt lgkmcnt(8)
	v_mfma_f32_16x16x32_bf16 v[28:31], v[140:143], v[92:95], v[28:31]
	ds_read_b64_tr_b16 v[128:129], v231 offset:49152
	ds_read_b64_tr_b16 v[130:131], v232 offset:49664
	ds_read_b64_tr_b16 v[132:133], v231 offset:53248
	ds_read_b64_tr_b16 v[134:135], v232 offset:53760
	ds_read_b64_tr_b16 v[136:137], v231 offset:57344
	ds_read_b64_tr_b16 v[138:139], v232 offset:57856
	ds_read_b64_tr_b16 v[140:141], v231 offset:61440
	ds_read_b64_tr_b16 v[142:143], v232 offset:61952
	s_waitcnt lgkmcnt(14)
	v_mfma_f32_16x16x32_bf16 v[20:23], v[156:159], v[72:75], v[20:23]
	s_waitcnt lgkmcnt(12)
	v_mfma_f32_16x16x32_bf16 v[20:23], v[194:197], v[80:83], v[20:23]
	s_waitcnt lgkmcnt(10)
	v_mfma_f32_16x16x32_bf16 v[20:23], v[234:237], v[88:91], v[20:23]
	s_waitcnt lgkmcnt(8)
	v_mfma_f32_16x16x32_bf16 v[20:23], v[242:245], v[92:95], v[20:23]
	ds_read_b64_tr_b16 v[156:157], v233 offset:49152
	ds_read_b64_tr_b16 v[158:159], v241 offset:49664
	ds_read_b64_tr_b16 v[194:195], v233 offset:53248
	ds_read_b64_tr_b16 v[196:197], v241 offset:53760
	ds_read_b64_tr_b16 v[234:235], v233 offset:57344
	ds_read_b64_tr_b16 v[236:237], v241 offset:57856
	ds_read_b64_tr_b16 v[242:243], v233 offset:61440
	ds_read_b64_tr_b16 v[244:245], v241 offset:61952
	s_waitcnt lgkmcnt(14)
	v_mfma_f32_16x16x32_bf16 v[16:19], v[128:131], v[72:75], v[16:19]
	s_waitcnt lgkmcnt(0)
	s_barrier
	v_cndmask_b32_e64 v128, 0, 1, s[44:45]
	v_cmp_ne_u32_e64 s[34:35], 1, v128
	s_waitcnt lgkmcnt(12)
	v_mfma_f32_16x16x32_bf16 v[16:19], v[132:135], v[80:83], v[16:19]
	v_lshl_add_u64 v[128:129], v[148:149], 0, s[42:43]
	v_lshl_add_u64 v[130:131], v[150:151], 0, s[42:43]
	s_cbranch_vccnz .Lscan0_nodma
	s_waitcnt vmcnt(8)
	s_branch .Lscan0_wdone

; __device__ __forceinline__ void scan_phase(const Frame& F, const bf16_t* Q, const bf16_t* K, const bf16_t* V, const bf16_t* PB, bf16_t* OF, bf16_t* OB, int half) {
;     ...
;                 {
;                     bf16x8 Rf[2];
; #pragma unroll
;                     for (int ks = 0; ks < 2; ++ks) { const f32x4 r0v = Rt[4 * p + 2 * ks], r1v = Rt[4 * p + 2 * ks + 1];
;                         const u32x4 wvv = {cvt_pk_bf16(r0v[0], r0v[1]), cvt_pk_bf16(r0v[2], r0v[3]), cvt_pk_bf16(r1v[0], r1v[1]), cvt_pk_bf16(r1v[2], r1v[3])};
;                         Rf[ks] = __builtin_bit_cast(bf16x8, wvv); }
;                     u32x4 qf[2][2];
;     ...
;                     SCAN_QREAD(0, 0);
; #pragma unroll
;                     for (int it = 0; it < 8; ++it) { if (it < 7) SCAN_QREAD((it + 1) & 1, it + 1);
; #pragma unroll
;                         for (int ks = 0; ks < 2; ++ks) Ot[it] = __builtin_amdgcn_mfma_f32_16x16x32_bf16(Rf[ks], __builtin_bit_cast(bf16x8, qf[it & 1][ks]), Ot[it], 0, 0, 0); }
;     ...
;                     __builtin_amdgcn_sched_group_barrier(0x100, 4, 0);
;                     __builtin_amdgcn_sched_group_barrier(0x100, 4, 0); __builtin_amdgcn_sched_group_barrier(0x8, 2, 0);
;                     __builtin_amdgcn_sched_group_barrier(0x100, 4, 0); __builtin_amdgcn_sched_group_barrier(0x8, 2, 0);
;                     __builtin_amdgcn_sched_group_barrier(0x100, 4, 0); __builtin_amdgcn_sched_group_barrier(0x8, 2, 0);
;                     __builtin_amdgcn_sched_group_barrier(0x100, 4, 0); __builtin_amdgcn_sched_group_barrier(0x8, 2, 0);
;                     __builtin_amdgcn_sched_group_barrier(0x100, 4, 0); __builtin_amdgcn_sched_group_barrier(0x8, 2, 0);
;                     __builtin_amdgcn_sched_group_barrier(0x100, 4, 0); __builtin_amdgcn_sched_group_barrier(0x8, 2, 0);
;                     __builtin_amdgcn_sched_group_barrier(0x100, 4, 0); __builtin_amdgcn_sched_group_barrier(0x8, 2, 0);
;                     __builtin_amdgcn_sched_group_barrier(0x8, 2, 0);
;                 }
;                 __builtin_amdgcn_sched_barrier(0);
;                 { s16x4 kl[2][4], kh[2][4];
;     ...
;                 SCAN_KREAD(0, 0);
; #pragma unroll
;                 for (int mt = 0; mt < 4; ++mt) { if (mt < 3) SCAN_KREAD((mt + 1) & 1, mt + 1);
;                     f32x4 acc = Rt[4 * p + mt] * c1;
; #pragma unroll
.LBB0_982:
	v_cvt_pk_bf16_f32 v132, v12, v13
	v_cvt_pk_bf16_f32 v133, v14, v15
	v_cvt_pk_bf16_f32 v134, v8, v9
	v_cvt_pk_bf16_f32 v135, v10, v11
	v_cvt_pk_bf16_f32 v136, v4, v5
	v_cvt_pk_bf16_f32 v137, v6, v7
	v_cvt_pk_bf16_f32 v138, v0, v1
	v_cvt_pk_bf16_f32 v139, v2, v3
	ds_read_b64 v[140:141], v223
	ds_read_b64 v[142:143], v224
	ds_read_b64 v[156:157], v225
	ds_read_b64 v[158:159], v226
	ds_read_b64 v[194:195], v223 offset:2048
	ds_read_b64 v[196:197], v224 offset:2048
	ds_read_b64 v[234:235], v225 offset:2048
	ds_read_b64 v[236:237], v226 offset:2048
	s_waitcnt lgkmcnt(6)
	v_mfma_f32_16x16x32_bf16 v[96:99], v[132:135], v[140:143], v[96:99]
	s_waitcnt lgkmcnt(4)
	v_mfma_f32_16x16x32_bf16 v[96:99], v[136:139], v[156:159], v[96:99]
	ds_read_b64 v[140:141], v223 offset:4096
	ds_read_b64 v[142:143], v224 offset:4096
	ds_read_b64 v[156:157], v225 offset:4096
	ds_read_b64 v[158:159], v226 offset:4096
	s_waitcnt lgkmcnt(6)
	v_mfma_f32_16x16x32_bf16 v[100:103], v[132:135], v[194:197], v[100:103]
	s_waitcnt lgkmcnt(4)
	v_mfma_f32_16x16x32_bf16 v[100:103], v[136:139], v[234:237], v[100:103]
	ds_read_b64 v[194:195], v223 offset:6144
	ds_read_b64 v[196:197], v224 offset:6144
	ds_read_b64 v[234:235], v225 offset:6144
	ds_read_b64 v[236:237], v226 offset:6144
	s_waitcnt lgkmcnt(6)
	v_mfma_f32_16x16x32_bf16 v[104:107], v[132:135], v[140:143], v[104:107]
	s_waitcnt lgkmcnt(4)
	v_mfma_f32_16x16x32_bf16 v[104:107], v[136:139], v[156:159], v[104:107]
	ds_read_b64 v[140:141], v223 offset:8192
	ds_read_b64 v[142:143], v224 offset:8192
	ds_read_b64 v[156:157], v225 offset:8192
	ds_read_b64 v[158:159], v226 offset:8192
	s_waitcnt lgkmcnt(6)
	v_mfma_f32_16x16x32_bf16 v[108:111], v[132:135], v[194:197], v[108:111]
	s_waitcnt lgkmcnt(4)
	v_mfma_f32_16x16x32_bf16 v[108:111], v[136:139], v[234:237], v[108:111]
	ds_read_b64 v[194:195], v223 offset:10240
	ds_read_b64 v[196:197], v224 offset:10240
	ds_read_b64 v[234:235], v225 offset:10240
	ds_read_b64 v[236:237], v226 offset:10240
	s_waitcnt lgkmcnt(6)
	v_mfma_f32_16x16x32_bf16 v[112:115], v[132:135], v[140:143], v[112:115]
	s_waitcnt lgkmcnt(4)
	v_mfma_f32_16x16x32_bf16 v[112:115], v[136:139], v[156:159], v[112:115]
	ds_read_b64 v[140:141], v223 offset:12288
	ds_read_b64 v[142:143], v224 offset:12288
	ds_read_b64 v[156:157], v225 offset:12288
	ds_read_b64 v[158:159], v226 offset:12288
	s_waitcnt lgkmcnt(6)
	v_mfma_f32_16x16x32_bf16 v[116:119], v[132:135], v[194:197], v[116:119]
	s_waitcnt lgkmcnt(4)
	v_mfma_f32_16x16x32_bf16 v[116:119], v[136:139], v[234:237], v[116:119]
	ds_read_b64 v[194:195], v223 offset:14336
	ds_read_b64 v[196:197], v224 offset:14336
	ds_read_b64 v[234:235], v225 offset:14336
	ds_read_b64 v[236:237], v226 offset:14336
	s_waitcnt lgkmcnt(6)
	v_mfma_f32_16x16x32_bf16 v[120:123], v[132:135], v[140:143], v[120:123]
	s_waitcnt lgkmcnt(4)
	v_mfma_f32_16x16x32_bf16 v[120:123], v[136:139], v[156:159], v[120:123]
	s_waitcnt lgkmcnt(2)
	v_mfma_f32_16x16x32_bf16 v[124:127], v[132:135], v[194:197], v[124:127]
	s_waitcnt lgkmcnt(0)
	v_mfma_f32_16x16x32_bf16 v[124:127], v[136:139], v[234:237], v[124:127]
	ds_read_b64_tr_b16 v[132:133], v227 offset:32768
	ds_read_b64_tr_b16 v[134:135], v228 offset:33280
	ds_read_b64_tr_b16 v[136:137], v227 offset:36864
	ds_read_b64_tr_b16 v[138:139], v228 offset:37376
	v_mov_b32_e32 v145, v144
	ds_read_b64_tr_b16 v[140:141], v227 offset:40960
	ds_read_b64_tr_b16 v[142:143], v228 offset:41472
	v_mul_f32_e32 v14, v144, v14
	v_mul_f32_e32 v15, v145, v15
	v_mul_f32_e32 v12, v146, v12
	v_mul_f32_e32 v13, v147, v13
	ds_read_b64_tr_b16 v[156:157], v227 offset:45056
	ds_read_b64_tr_b16 v[158:159], v228 offset:45568
	ds_read_b64_tr_b16 v[194:195], v229 offset:32768
	ds_read_b64_tr_b16 v[196:197], v230 offset:33280
	ds_read_b64_tr_b16 v[234:235], v229 offset:36864
	ds_read_b64_tr_b16 v[236:237], v230 offset:37376
	ds_read_b64_tr_b16 v[242:243], v229 offset:40960
	ds_read_b64_tr_b16 v[244:245], v230 offset:41472
	ds_read_b64_tr_b16 v[246:247], v229 offset:45056
	ds_read_b64_tr_b16 v[248:249], v230 offset:45568
	s_waitcnt lgkmcnt(14)
	v_mfma_f32_16x16x32_bf16 v[12:15], v[132:135], v[72:75], v[12:15]
	v_mul_f32_e64 v10, v144, v10
	v_mul_f32_e64 v11, v145, v11
	v_mul_f32_e32 v8, v146, v8
	v_mul_f32_e32 v9, v147, v9
	v_mul_f32_e32 v6, v144, v6
	v_mul_f32_e32 v7, v145, v7
	s_waitcnt lgkmcnt(12)
	v_mfma_f32_16x16x32_bf16 v[12:15], v[136:139], v[80:83], v[12:15]
	v_mul_f32_e64 v4, v146, v4
	v_mul_f32_e64 v5, v147, v5
	v_mul_f32_e32 v2, v144, v2
	v_mul_f32_e32 v3, v145, v3
	v_mul_f32_e32 v0, v146, v0
	v_mul_f32_e32 v1, v147, v1
	s_waitcnt lgkmcnt(10)
	v_mfma_f32_16x16x32_bf16 v[12:15], v[140:143], v[88:91], v[12:15]
	s_and_b64 vcc, exec, s[34:35]
	s_waitcnt lgkmcnt(8)
	v_mfma_f32_16x16x32_bf16 v[12:15], v[156:159], v[92:95], v[12:15]
	ds_read_b64_tr_b16 v[132:133], v231 offset:32768
	ds_read_b64_tr_b16 v[134:135], v232 offset:33280
	ds_read_b64_tr_b16 v[136:137], v231 offset:36864
	ds_read_b64_tr_b16 v[138:139], v232 offset:37376
	ds_read_b64_tr_b16 v[140:141], v231 offset:40960
	ds_read_b64_tr_b16 v[142:143], v232 offset:41472
	ds_read_b64_tr_b16 v[156:157], v231 offset:45056
	ds_read_b64_tr_b16 v[158:159], v232 offset:45568
	s_waitcnt lgkmcnt(14)
	v_mfma_f32_16x16x32_bf16 v[8:11], v[194:197], v[72:75], v[8:11]
	s_waitcnt lgkmcnt(12)
	v_mfma_f32_16x16x32_bf16 v[8:11], v[234:237], v[80:83], v[8:11]
	s_waitcnt lgkmcnt(10)
	v_mfma_f32_16x16x32_bf16 v[8:11], v[242:245], v[88:91], v[8:11]
	s_waitcnt lgkmcnt(8)
	v_mfma_f32_16x16x32_bf16 v[8:11], v[246:249], v[92:95], v[8:11]
	ds_read_b64_tr_b16 v[194:195], v233 offset:32768
	ds_read_b64_tr_b16 v[196:197], v241 offset:33280
	ds_read_b64_tr_b16 v[234:235], v233 offset:36864
	ds_read_b64_tr_b16 v[236:237], v241 offset:37376
	ds_read_b64_tr_b16 v[242:243], v233 offset:40960
	ds_read_b64_tr_b16 v[244:245], v241 offset:41472
	ds_read_b64_tr_b16 v[246:247], v233 offset:45056
	ds_read_b64_tr_b16 v[248:249], v241 offset:45568
	s_waitcnt lgkmcnt(14)
	v_mfma_f32_16x16x32_bf16 v[4:7], v[132:135], v[72:75], v[4:7]
	s_waitcnt lgkmcnt(0)
	s_barrier
; __device__ __forceinline__ bf16x8 pack8(s16x4 lo, s16x4 hi) { return (bf16x8){lo[0], lo[1], lo[2], lo[3], hi[0], hi[1], hi[2], hi[3]}; }
; #define SCAN_BAR() asm volatile("s_waitcnt lgkmcnt(0)\n\ts_barrier" ::: "memory")
; #define SCAN_LOAD_QK(cc, pq) do { const size_t u0_ = (rb + (size_t)(cc) * 128) * 2048 + head * 256 + (pq) * 64;     \
;             _Pragma("unroll") for (int ii = 0; ii < 2; ++ii) { rq[ii] = *(const GAS u32x4*)(Q + u0_ + (size_t)ii * 64 * 2048 + lqk_l); rk[ii] = *(const GAS u32x4*)(K + u0_ + (size_t)ii * 64 * 2048 + lqk_l); } } while (0)
; __device__ __forceinline__ void scan_phase(const Frame& F, const bf16_t* Q, const bf16_t* K, const bf16_t* V, const bf16_t* PB, bf16_t* OF, bf16_t* OB, int half) {
;     ...
;         unsigned pmk[2][4];
; #pragma unroll
;         for (int par = 0; par < 2; ++par) { int nk = 16 * par + l15 - 8 * quad + 1; nk = nk < 0 ? 0 : (nk > 8 ? 8 : nk);
; #pragma unroll
;             for (int d_ = 0; d_ < 4; ++d_) { const unsigned mf = ((2 * d_ < nk) ? 0xffffu : 0u) | ((2 * d_ + 1 < nk) ? 0xffff0000u : 0u); pmk[par][d_] = dir ? ~mf : mf; } }
;         { const int c0 = dir ? nchunk - 1 : 0; SCAN_DMA_VP(c0); SCAN_LOAD_QK(c0, 0); SCAN_WRITE_QK(0); SCAN_LOAD_QK(c0, 1); }
;         SCAN_BAR();
;         for (int s = 0; s < nchunk; ++s) {
;             const int c = dir ? nchunk - 1 - s : s, cn = dir ? nchunk - 2 - s : s + 1; const size_t r0 = rb + (size_t)c * 128; const bool more = s + 1 < nchunk;
;             f32x4 Ot[8]; bf16x8 Vf[4];
; #pragma unroll
;             for (int i = 0; i < 8; ++i) Ot[i] = (f32x4){0.f, 0.f, 0.f, 0.f};
;             int quad_l = quad, l15_l = l15; asm volatile("" : "+v"(quad_l), "+v"(l15_l));
; #pragma unroll
;             for (int p = 0; p < 4; ++p) {
;                 if (p < 3 || more) SCAN_WRITE_QK((p + 1) & 1);
;                 if (p == 1 && more) SCAN_DMA_VP(cn);
;                 if (p < 2) SCAN_LOAD_QK(c, p + 2); else if (more) SCAN_LOAD_QK(cn, p - 2);
;     ...
;                 for (int mt = 0; mt < 4; ++mt) { if (mt < 3) SCAN_KREAD((mt + 1) & 1, mt + 1);
;                     f32x4 acc = Rt[4 * p + mt] * c1;
; #pragma unroll
;                     for (int ks = 0; ks < 4; ++ks) acc = __builtin_amdgcn_mfma_f32_16x16x32_bf16(pack8(kl[mt & 1][ks], kh[mt & 1][ks]), Vf[ks], acc, 0, 0, 0);
;                     Rt[4 * p + mt] = acc; }
	s_waitcnt lgkmcnt(12)
	v_mfma_f32_16x16x32_bf16 v[4:7], v[136:139], v[80:83], v[4:7]
	s_waitcnt lgkmcnt(10)
	v_mfma_f32_16x16x32_bf16 v[4:7], v[140:143], v[88:91], v[4:7]
	s_waitcnt lgkmcnt(8)
	v_mfma_f32_16x16x32_bf16 v[4:7], v[156:159], v[92:95], v[4:7]
	s_waitcnt lgkmcnt(6)
	v_mfma_f32_16x16x32_bf16 v[0:3], v[194:197], v[72:75], v[0:3]
	s_waitcnt lgkmcnt(4)
	v_mfma_f32_16x16x32_bf16 v[0:3], v[234:237], v[80:83], v[0:3]
	s_waitcnt lgkmcnt(2)
	v_mfma_f32_16x16x32_bf16 v[0:3], v[242:245], v[88:91], v[0:3]
	s_waitcnt lgkmcnt(0)
	v_mfma_f32_16x16x32_bf16 v[0:3], v[246:249], v[92:95], v[0:3]
	s_cbranch_vccnz .LBB0_977
	s_waitcnt vmcnt(3)
	ds_write_b128 v214, v[64:67]
	s_waitcnt vmcnt(2)
	ds_write_b128 v214, v[68:71] offset:32768
	s_waitcnt vmcnt(1)
	ds_write_b128 v214, v[76:79] offset:8192
	s_waitcnt vmcnt(0)
	ds_write_b128 v214, v[84:87] offset:40960
	v_add_co_u32_e32 v64, vcc, 0x10700000, v130
	s_nop 1
	v_addc_co_u32_e32 v65, vcc, 0, v131, vcc
	v_add_co_u32_e32 v68, vcc, 0x4a800000, v128
	global_load_dwordx4 v[64:67], v[64:65], off offset:128
	s_nop 0
	v_addc_co_u32_e32 v69, vcc, 0, v129, vcc
	v_add_co_u32_e32 v76, vcc, 0x10740000, v130
	global_load_dwordx4 v[68:71], v[68:69], off offset:128
	s_nop 0
	v_addc_co_u32_e32 v77, vcc, 0, v131, vcc
	v_add_co_u32_e32 v84, vcc, 0x4a840000, v128
	global_load_dwordx4 v[76:79], v[76:77], off offset:128
	s_nop 0
	v_addc_co_u32_e32 v85, vcc, 0, v129, vcc
	global_load_dwordx4 v[84:87], v[84:85], off offset:128
	s_branch .LBB0_977

; __device__ __forceinline__ void scan_phase(const Frame& F, const bf16_t* Q, const bf16_t* K, const bf16_t* V, const bf16_t* PB, bf16_t* OF, bf16_t* OB, int half) {
;     ...
;                 {
;                     bf16x8 Rf[2];
; #pragma unroll
;                     for (int ks = 0; ks < 2; ++ks) { const f32x4 r0v = Rt[4 * p + 2 * ks], r1v = Rt[4 * p + 2 * ks + 1];
;                         const u32x4 wvv = {cvt_pk_bf16(r0v[0], r0v[1]), cvt_pk_bf16(r0v[2], r0v[3]), cvt_pk_bf16(r1v[0], r1v[1]), cvt_pk_bf16(r1v[2], r1v[3])};
;                         Rf[ks] = __builtin_bit_cast(bf16x8, wvv); }
;                     u32x4 qf[2][2];
;     ...
;                     SCAN_QREAD(0, 0);
; #pragma unroll
;                     for (int it = 0; it < 8; ++it) { if (it < 7) SCAN_QREAD((it + 1) & 1, it + 1);
; #pragma unroll
;                         for (int ks = 0; ks < 2; ++ks) Ot[it] = __builtin_amdgcn_mfma_f32_16x16x32_bf16(Rf[ks], __builtin_bit_cast(bf16x8, qf[it & 1][ks]), Ot[it], 0, 0, 0); }
;     ...
;                     __builtin_amdgcn_sched_group_barrier(0x100, 4, 0);
;                     __builtin_amdgcn_sched_group_barrier(0x100, 4, 0); __builtin_amdgcn_sched_group_barrier(0x8, 2, 0);
;                     __builtin_amdgcn_sched_group_barrier(0x100, 4, 0); __builtin_amdgcn_sched_group_barrier(0x8, 2, 0);
;                     __builtin_amdgcn_sched_group_barrier(0x100, 4, 0); __builtin_amdgcn_sched_group_barrier(0x8, 2, 0);
;                     __builtin_amdgcn_sched_group_barrier(0x100, 4, 0); __builtin_amdgcn_sched_group_barrier(0x8, 2, 0);
;                     __builtin_amdgcn_sched_group_barrier(0x100, 4, 0); __builtin_amdgcn_sched_group_barrier(0x8, 2, 0);
;                     __builtin_amdgcn_sched_group_barrier(0x100, 4, 0); __builtin_amdgcn_sched_group_barrier(0x8, 2, 0);
;                     __builtin_amdgcn_sched_group_barrier(0x100, 4, 0); __builtin_amdgcn_sched_group_barrier(0x8, 2, 0);
;                     __builtin_amdgcn_sched_group_barrier(0x8, 2, 0);
;                 }
;                 __builtin_amdgcn_sched_barrier(0);
;                 { s16x4 kl[2][4], kh[2][4];
;     ...
;                 SCAN_KREAD(0, 0);
; #pragma unroll
;                 for (int mt = 0; mt < 4; ++mt) { if (mt < 3) SCAN_KREAD((mt + 1) & 1, mt + 1);
;                     f32x4 acc = Rt[4 * p + mt] * c1;
; #pragma unroll
.LBB0_987:
	v_add_u32_e32 v128, 1, v192
	v_cvt_f32_i32_e32 v229, v128
	v_cvt_pk_bf16_f32 v140, v48, v49
	v_cvt_pk_bf16_f32 v141, v50, v51
	v_cvt_pk_bf16_f32 v142, v52, v53
	v_cvt_pk_bf16_f32 v143, v54, v55
	v_cvt_pk_bf16_f32 v150, v56, v57
	v_cvt_pk_bf16_f32 v151, v58, v59
	v_cvt_pk_bf16_f32 v152, v60, v61
	v_cvt_pk_bf16_f32 v153, v62, v63
	ds_read_b64 v[128:129], v217 offset:16384
	ds_read_b64 v[130:131], v218 offset:16384
	ds_read_b64 v[132:133], v219 offset:16384
	ds_read_b64 v[134:135], v220 offset:16384
	ds_read_b64 v[136:137], v217 offset:18432
	ds_read_b64 v[138:139], v218 offset:18432
	ds_read_b64 v[194:195], v219 offset:18432
	ds_read_b64 v[196:197], v220 offset:18432
	s_waitcnt lgkmcnt(6)
	v_mfma_f32_16x16x32_bf16 v[96:99], v[140:143], v[128:131], v[96:99]
	s_waitcnt lgkmcnt(4)
	v_mfma_f32_16x16x32_bf16 v[132:135], v[150:153], v[132:135], v[96:99]
	s_nop 5
	ds_read_b64 v[96:97], v217 offset:20480
	ds_read_b64 v[98:99], v218 offset:20480
	ds_read_b64 v[128:129], v219 offset:20480
	ds_read_b64 v[130:131], v220 offset:20480
	s_waitcnt lgkmcnt(6)
	v_mfma_f32_16x16x32_bf16 v[100:103], v[140:143], v[136:139], v[100:103]
	s_waitcnt lgkmcnt(4)
	v_mfma_f32_16x16x32_bf16 v[136:139], v[150:153], v[194:197], v[100:103]
	s_nop 5
	ds_read_b64 v[100:101], v217 offset:22528
	ds_read_b64 v[102:103], v218 offset:22528
	ds_read_b64 v[194:195], v219 offset:22528
	ds_read_b64 v[196:197], v220 offset:22528
	s_waitcnt lgkmcnt(6)
	v_mfma_f32_16x16x32_bf16 v[96:99], v[140:143], v[96:99], v[104:107]
	s_waitcnt lgkmcnt(4)
	v_mfma_f32_16x16x32_bf16 v[128:131], v[150:153], v[128:131], v[96:99]
	s_nop 5
	ds_read_b64 v[96:97], v217 offset:24576
	ds_read_b64 v[98:99], v218 offset:24576
	ds_read_b64 v[104:105], v219 offset:24576
	ds_read_b64 v[106:107], v220 offset:24576
	s_waitcnt lgkmcnt(6)
	v_mfma_f32_16x16x32_bf16 v[100:103], v[140:143], v[100:103], v[108:111]
	s_waitcnt lgkmcnt(4)
	v_mfma_f32_16x16x32_bf16 v[108:111], v[150:153], v[194:197], v[100:103]
	s_nop 5
	ds_read_b64 v[100:101], v217 offset:26624
	ds_read_b64 v[102:103], v218 offset:26624
	ds_read_b64 v[194:195], v219 offset:26624
	ds_read_b64 v[196:197], v220 offset:26624
	s_waitcnt lgkmcnt(6)
	v_mfma_f32_16x16x32_bf16 v[96:99], v[140:143], v[96:99], v[112:115]
	s_waitcnt lgkmcnt(4)
	v_mfma_f32_16x16x32_bf16 v[104:107], v[150:153], v[104:107], v[96:99]
	s_nop 5
	ds_read_b64 v[96:97], v217 offset:28672
	ds_read_b64 v[98:99], v218 offset:28672
	ds_read_b64 v[112:113], v219 offset:28672
	ds_read_b64 v[114:115], v220 offset:28672
	s_waitcnt lgkmcnt(6)
	v_mfma_f32_16x16x32_bf16 v[100:103], v[140:143], v[100:103], v[116:119]
	s_waitcnt lgkmcnt(4)
	v_mfma_f32_16x16x32_bf16 v[100:103], v[150:153], v[194:197], v[100:103]
	s_nop 0
	ds_read_b64 v[116:117], v217 offset:30720
	ds_read_b64 v[118:119], v218 offset:30720
	ds_read_b64 v[194:195], v219 offset:30720
	ds_read_b64 v[196:197], v220 offset:30720
	s_waitcnt lgkmcnt(6)
	v_mfma_f32_16x16x32_bf16 v[96:99], v[140:143], v[96:99], v[120:123]
	s_waitcnt lgkmcnt(4)
	v_mfma_f32_16x16x32_bf16 v[96:99], v[150:153], v[112:115], v[96:99]
	s_waitcnt lgkmcnt(2)
	v_mfma_f32_16x16x32_bf16 v[112:115], v[140:143], v[116:119], v[124:127]
	s_waitcnt lgkmcnt(0)
	v_mfma_f32_16x16x32_bf16 v[112:115], v[150:153], v[194:197], v[112:115]
	ds_read_b64_tr_b16 v[116:117], v221 offset:49152
	ds_read_b64_tr_b16 v[118:119], v222 offset:49664
	ds_read_b64_tr_b16 v[120:121], v221 offset:53248
	ds_read_b64_tr_b16 v[122:123], v222 offset:53760
	ds_read_b64_tr_b16 v[124:125], v221 offset:57344
	ds_read_b64_tr_b16 v[126:127], v222 offset:57856
	v_mul_f32_e32 v50, v144, v50
	v_mul_f32_e32 v51, v145, v51
	v_mul_f32_e32 v48, v146, v48
	v_mul_f32_e32 v49, v147, v49
	ds_read_b64_tr_b16 v[140:141], v221 offset:61440
	ds_read_b64_tr_b16 v[142:143], v222 offset:61952
	ds_read_b64_tr_b16 v[150:151], v223 offset:49152
	ds_read_b64_tr_b16 v[152:153], v224 offset:49664
	ds_read_b64_tr_b16 v[194:195], v223 offset:53248
	ds_read_b64_tr_b16 v[196:197], v224 offset:53760
	ds_read_b64_tr_b16 v[218:219], v223 offset:57344
	ds_read_b64_tr_b16 v[220:221], v224 offset:57856
	ds_read_b64_tr_b16 v[230:231], v223 offset:61440
	ds_read_b64_tr_b16 v[232:233], v224 offset:61952
	s_waitcnt lgkmcnt(14)
	v_mfma_f32_16x16x32_bf16 v[48:51], v[116:119], v[72:75], v[48:51]
	v_mul_f32_e64 v54, v144, v54
	v_mul_f32_e64 v55, v145, v55
	v_mul_f32_e32 v52, v146, v52
	v_mul_f32_e32 v53, v147, v53
	v_mul_f32_e32 v58, v144, v58
	v_mul_f32_e32 v59, v145, v59
	s_waitcnt lgkmcnt(12)
	v_mfma_f32_16x16x32_bf16 v[48:51], v[120:123], v[80:83], v[48:51]
	v_mul_f32_e64 v56, v146, v56
	v_mul_f32_e64 v57, v147, v57
	v_mul_f32_e32 v62, v144, v62
	v_mul_f32_e32 v63, v145, v63
	v_mul_f32_e32 v60, v146, v60
	v_mul_f32_e32 v61, v147, v61
	s_waitcnt lgkmcnt(10)
	v_mfma_f32_16x16x32_bf16 v[48:51], v[124:127], v[88:91], v[48:51]
	s_add_u32 s12, s62, s41
	v_lshl_add_u32 v192, v192, 12, v213
	s_addc_u32 s13, s63, s42
	s_waitcnt lgkmcnt(8)
	v_mfma_f32_16x16x32_bf16 v[48:51], v[140:143], v[92:95], v[48:51]
	ds_read_b64_tr_b16 v[116:117], v225 offset:49152
	ds_read_b64_tr_b16 v[118:119], v226 offset:49664
	ds_read_b64_tr_b16 v[120:121], v225 offset:53248
	ds_read_b64_tr_b16 v[122:123], v226 offset:53760
	ds_read_b64_tr_b16 v[124:125], v225 offset:57344
	ds_read_b64_tr_b16 v[126:127], v226 offset:57856
	ds_read_b64_tr_b16 v[140:141], v225 offset:61440
	ds_read_b64_tr_b16 v[142:143], v226 offset:61952
	s_waitcnt lgkmcnt(14)
	v_mfma_f32_16x16x32_bf16 v[52:55], v[150:153], v[72:75], v[52:55]
	s_add_u32 s30, s30, 0x100000
	s_addc_u32 s31, s31, 0
	s_add_u32 s41, s41, 0x100000
	s_waitcnt lgkmcnt(12)
; #define GAS __attribute__((address_space(1)))
; __device__ __forceinline__ unsigned cvt_pk_bf16(float lo, float hi) { unsigned r; asm volatile("v_cvt_pk_bf16_f32 %0, %1, %2" : "=v"(r) : "v"(lo), "v"(hi)); return r; }
; __device__ __forceinline__ bf16x8 pack8(s16x4 lo, s16x4 hi) { return (bf16x8){lo[0], lo[1], lo[2], lo[3], hi[0], hi[1], hi[2], hi[3]}; }
; #define SCAN_BAR() asm volatile("s_waitcnt lgkmcnt(0)\n\ts_barrier" ::: "memory")
; #define SCAN_KREAD(b_, mt_) do { _Pragma("unroll") for (int ks = 0; ks < 4; ++ks) { const int ko = ((p & 1) ? LK1 : LK0) + 32 * ks * QS; kl[b_][ks] = tr_read(bKlo[mt_] + ko); kh[b_][ks] = tr_read(bKhi[mt_] + ko); } } while (0)
; __device__ __forceinline__ void scan_phase(const Frame& F, const bf16_t* Q, const bf16_t* K, const bf16_t* V, const bf16_t* PB, bf16_t* OF, bf16_t* OB, int half) {
;     ...
;                 for (int mt = 0; mt < 4; ++mt) { if (mt < 3) SCAN_KREAD((mt + 1) & 1, mt + 1);
;                     f32x4 acc = Rt[4 * p + mt] * c1;
; #pragma unroll
;                     for (int ks = 0; ks < 4; ++ks) acc = __builtin_amdgcn_mfma_f32_16x16x32_bf16(pack8(kl[mt & 1][ks], kh[mt & 1][ks]), Vf[ks], acc, 0, 0, 0);
;                     Rt[4 * p + mt] = acc; }
;     ...
;                 __builtin_amdgcn_sched_group_barrier(0x100, 8, 0);
;                 __builtin_amdgcn_sched_group_barrier(0x100, 8, 0); __builtin_amdgcn_sched_group_barrier(0x8, 4, 0);
;                 __builtin_amdgcn_sched_group_barrier(0x100, 8, 0); __builtin_amdgcn_sched_group_barrier(0x8, 4, 0);
;                 __builtin_amdgcn_sched_group_barrier(0x100, 8, 0); __builtin_amdgcn_sched_group_barrier(0x8, 4, 0);
;                 __builtin_amdgcn_sched_group_barrier(0x8, 4, 0);
;                 }
;                 if (p == 3) {
;                     bf16_t* ob_ = O + r0 * 4096 + head * 512 + vq * 128; const unsigned lo_ = (unsigned)(l15_l * 4096 + 16 * wv + 4 * quad);
;                     float fi = __builtin_amdgcn_exp2f(lg2 * (float)(dir ? 128 - l15_l : l15_l + 1));
; #pragma unroll
;                     for (int it = 0; it < 8; ++it) {
;                         *(GAS u32x2*)(ob_ + (size_t)(16 * it) * 4096 + lo_) = (u32x2){cvt_pk_bf16(Ot[it][0] * fi, Ot[it][1] * fi), cvt_pk_bf16(Ot[it][2] * fi, Ot[it][3] * fi)}; fi *= gm16; }
;                 }
;                 SCAN_BAR();
	v_mfma_f32_16x16x32_bf16 v[52:55], v[194:197], v[80:83], v[52:55]
	s_addc_u32 s42, s42, 0
	v_lshl_add_u64 v[148:149], v[148:149], 0, s[24:25]
	s_cmp_eq_u32 s73, s43
	s_waitcnt lgkmcnt(10)
	v_mfma_f32_16x16x32_bf16 v[52:55], v[218:221], v[88:91], v[52:55]
	s_mov_b32 s44, s43
	s_waitcnt lgkmcnt(8)
	v_mfma_f32_16x16x32_bf16 v[52:55], v[230:233], v[92:95], v[52:55]
	ds_read_b64_tr_b16 v[150:151], v227 offset:49152
	ds_read_b64_tr_b16 v[152:153], v228 offset:49664
	ds_read_b64_tr_b16 v[194:195], v227 offset:53248
	ds_read_b64_tr_b16 v[196:197], v228 offset:53760
	ds_read_b64_tr_b16 v[218:219], v227 offset:57344
	ds_read_b64_tr_b16 v[220:221], v228 offset:57856
	ds_read_b64_tr_b16 v[222:223], v227 offset:61440
	ds_read_b64_tr_b16 v[224:225], v228 offset:61952
	s_waitcnt lgkmcnt(14)
	v_mfma_f32_16x16x32_bf16 v[56:59], v[116:119], v[72:75], v[56:59]
	s_waitcnt lgkmcnt(12)
	v_mfma_f32_16x16x32_bf16 v[56:59], v[120:123], v[80:83], v[56:59]
	s_waitcnt lgkmcnt(10)
	v_mfma_f32_16x16x32_bf16 v[56:59], v[124:127], v[88:91], v[56:59]
	s_waitcnt lgkmcnt(8)
	v_mfma_f32_16x16x32_bf16 v[56:59], v[140:143], v[92:95], v[56:59]
	s_waitcnt lgkmcnt(6)
	v_mfma_f32_16x16x32_bf16 v[60:63], v[150:153], v[72:75], v[60:63]
	v_mul_f32_e32 v72, s54, v229
	s_waitcnt lgkmcnt(4)
	v_mfma_f32_16x16x32_bf16 v[60:63], v[194:197], v[80:83], v[60:63]
	v_exp_f32_e32 v82, v72
	v_lshl_add_u64 v[72:73], v[192:193], 1, s[12:13]
	s_mov_b32 s12, 0x3a120000
	s_waitcnt lgkmcnt(2)
	v_mfma_f32_16x16x32_bf16 v[60:63], v[218:221], v[88:91], v[60:63]
	v_mul_f32_e32 v74, v82, v132
	v_mul_f32_e32 v75, v82, v133
	v_cvt_pk_bf16_f32 v74, v74, v75
	v_mul_f32_e32 v75, v82, v134
	v_mul_f32_e32 v80, v82, v135
	v_cvt_pk_bf16_f32 v75, v75, v80
	v_add_co_u32_e32 v80, vcc, s97, v72
	v_mul_f32_e32 v82, s37, v82
	s_nop 0
	v_addc_co_u32_e32 v81, vcc, 0, v73, vcc
	global_store_dwordx2 v[80:81], v[74:75], off
	v_mul_f32_e32 v74, v82, v136
	v_mul_f32_e32 v75, v82, v137
	v_cvt_pk_bf16_f32 v74, v74, v75
	v_mul_f32_e32 v75, v82, v138
	v_mul_f32_e32 v80, v82, v139
	v_cvt_pk_bf16_f32 v75, v75, v80
	v_add_co_u32_e32 v80, vcc, s12, v72
	v_mul_f32_e32 v82, s37, v82
	s_nop 0
	v_addc_co_u32_e32 v81, vcc, 0, v73, vcc
	global_store_dwordx2 v[80:81], v[74:75], off
	v_mul_f32_e32 v74, v82, v128
	v_mul_f32_e32 v75, v82, v129
	v_cvt_pk_bf16_f32 v74, v74, v75
	v_mul_f32_e32 v75, v82, v130
	v_mul_f32_e32 v80, v82, v131
	s_mov_b32 s12, 0x3a140000
	v_cvt_pk_bf16_f32 v75, v75, v80
	v_add_co_u32_e32 v80, vcc, s12, v72
	v_mul_f32_e32 v82, s37, v82
	s_nop 0
	v_addc_co_u32_e32 v81, vcc, 0, v73, vcc
	global_store_dwordx2 v[80:81], v[74:75], off
	v_mul_f32_e32 v74, v82, v108
	v_mul_f32_e32 v75, v82, v109
	v_cvt_pk_bf16_f32 v74, v74, v75
	v_mul_f32_e32 v75, v82, v110
	v_mul_f32_e32 v80, v82, v111
	s_mov_b32 s12, 0x3a160000
	v_cvt_pk_bf16_f32 v75, v75, v80
	v_add_co_u32_e32 v80, vcc, s12, v72
	v_mul_f32_e32 v82, s37, v82
	s_nop 0
	v_addc_co_u32_e32 v81, vcc, 0, v73, vcc
	global_store_dwordx2 v[80:81], v[74:75], off
	v_mul_f32_e32 v74, v82, v104
	v_mul_f32_e32 v75, v82, v105
	v_cvt_pk_bf16_f32 v74, v74, v75
	v_mul_f32_e32 v75, v82, v106
	v_mul_f32_e32 v80, v82, v107
	s_mov_b32 s12, 0x3a180000
	v_cvt_pk_bf16_f32 v75, v75, v80
	v_add_co_u32_e32 v80, vcc, s12, v72
	v_mul_f32_e32 v82, s37, v82
	s_nop 0
	v_addc_co_u32_e32 v81, vcc, 0, v73, vcc
	global_store_dwordx2 v[80:81], v[74:75], off
	v_mul_f32_e32 v74, v82, v100
	v_mul_f32_e32 v75, v82, v101
	v_cvt_pk_bf16_f32 v74, v74, v75
	v_mul_f32_e32 v75, v82, v102
	v_mul_f32_e32 v80, v82, v103
	s_mov_b32 s12, 0x3a1a0000
	v_cvt_pk_bf16_f32 v75, v75, v80
	v_add_co_u32_e32 v80, vcc, s12, v72
	v_mul_f32_e32 v82, s37, v82
	s_nop 0
	v_addc_co_u32_e32 v81, vcc, 0, v73, vcc
	global_store_dwordx2 v[80:81], v[74:75], off
	v_mul_f32_e32 v74, v82, v96
	v_mul_f32_e32 v75, v82, v97
	v_cvt_pk_bf16_f32 v74, v74, v75
	v_mul_f32_e32 v75, v82, v98
	v_mul_f32_e32 v80, v82, v99
	s_mov_b32 s12, 0x3a1c0000
	v_cvt_pk_bf16_f32 v75, v75, v80
	v_add_co_u32_e32 v80, vcc, s12, v72
	s_mov_b32 s12, 0x3a1e0000
	s_nop 0
	v_addc_co_u32_e32 v81, vcc, 0, v73, vcc
	global_store_dwordx2 v[80:81], v[74:75], off
	v_mul_f32_e32 v75, s37, v82
	v_mul_f32_e32 v74, v75, v112
	v_mul_f32_e32 v80, v75, v113
	v_add_co_u32_e32 v72, vcc, s12, v72
	v_cvt_pk_bf16_f32 v74, v74, v80
	v_mul_f32_e32 v80, v75, v114
	v_mul_f32_e32 v75, v75, v115
	v_addc_co_u32_e32 v73, vcc, 0, v73, vcc
	s_waitcnt lgkmcnt(0)
	v_mfma_f32_16x16x32_bf16 v[60:63], v[222:225], v[92:95], v[60:63]
	v_cvt_pk_bf16_f32 v75, v80, v75
	global_store_dwordx2 v[72:73], v[74:75], off
	s_waitcnt lgkmcnt(0)
	s_barrier
	s_cbranch_scc1 .LBB0_974
	.p2align 6
; #define LAS __attribute__((address_space(3)))
; __device__ __forceinline__ void scan_phase(const Frame& F, const bf16_t* Q, const bf16_t* K, const bf16_t* V, const bf16_t* PB, bf16_t* OF, bf16_t* OB, int half) {
;     ...
;         unsigned pmk[2][4];
; #pragma unroll
;         for (int par = 0; par < 2; ++par) { int nk = 16 * par + l15 - 8 * quad + 1; nk = nk < 0 ? 0 : (nk > 8 ? 8 : nk);
; #pragma unroll
;             for (int d_ = 0; d_ < 4; ++d_) { const unsigned mf = ((2 * d_ < nk) ? 0xffffu : 0u) | ((2 * d_ + 1 < nk) ? 0xffff0000u : 0u); pmk[par][d_] = dir ? ~mf : mf; } }
;         { const int c0 = dir ? nchunk - 1 : 0; SCAN_DMA_VP(c0); SCAN_LOAD_QK(c0, 0); SCAN_WRITE_QK(0); SCAN_LOAD_QK(c0, 1); }
;         SCAN_BAR();
;         for (int s = 0; s < nchunk; ++s) {
;             const int c = dir ? nchunk - 1 - s : s, cn = dir ? nchunk - 2 - s : s + 1; const size_t r0 = rb + (size_t)c * 128; const bool more = s + 1 < nchunk;
;             f32x4 Ot[8]; bf16x8 Vf[4];
; #pragma unroll
;             for (int i = 0; i < 8; ++i) Ot[i] = (f32x4){0.f, 0.f, 0.f, 0.f};
;             int quad_l = quad, l15_l = l15; asm volatile("" : "+v"(quad_l), "+v"(l15_l));
; #pragma unroll
;             for (int p = 0; p < 4; ++p) {
;                 if (p < 3 || more) SCAN_WRITE_QK((p + 1) & 1);
;                 if (p == 1 && more) SCAN_DMA_VP(cn);
;                 if (p < 2) SCAN_LOAD_QK(c, p + 2); else if (more) SCAN_LOAD_QK(cn, p - 2);
;                 if (p == 0) {
; #pragma unroll
;                     for (int ks = 0; ks < 4; ++ks) { const s16x4 lo = tr_read(bVlo + 32 * ks * 256), hi = tr_read(bVhi + 32 * ks * 256); Vf[ks] = pack8(lo, hi); }
;                     __builtin_amdgcn_sched_barrier(0);
;                     { u32x4 pwb[2];
;                       { constexpr int q0_ = pv_pair(dir, 0); pwb[0] = *(const LAS u32x4*)(bPk[q0_ & 3] + 16 * (q0_ >> 2) * 256); }
;                       __builtin_amdgcn_sched_group_barrier(0x100, 1, 0);
;                       mattn_sfor<0, 20>([&](auto n_) { constexpr int n = decltype(n_)::value, pr = pv_pair(dir, n), it = pr >> 2, ks = pr & 3, dks = ks - (it >> 1);
;                           if constexpr (n + 1 < 20) { constexpr int nx = pv_pair(dir, n + 1); pwb[(n + 1) & 1] = *(const LAS u32x4*)(bPk[nx & 3] + 16 * (nx >> 2) * 256); }
;                           u32x4 pw = pwb[n & 1];
.LBB0_988:
	v_lshl_add_u64 v[152:153], s[64:65], 0, v[148:149]
	s_mov_b32 s12, 0x10800000
	v_add_co_u32_e32 v72, vcc, s12, v152
	v_mov_b32_e32 v192, v161
	v_mov_b32_e32 v74, v162
	v_lshl_add_u64 v[150:151], s[62:63], 0, v[148:149]
	v_addc_co_u32_e32 v73, vcc, 0, v153, vcc
	s_mov_b32 s12, 0x4a900000
	global_load_dwordx4 v[96:99], v[72:73], off offset:256
	v_add_co_u32_e32 v72, vcc, s12, v150
	s_mov_b32 s12, 0x10840000
	s_nop 0
	v_addc_co_u32_e32 v73, vcc, 0, v151, vcc
	global_load_dwordx4 v[100:103], v[72:73], off offset:256
	v_add_co_u32_e32 v72, vcc, s12, v152
	s_mov_b32 s12, 0x4a940000
	s_nop 0
	v_addc_co_u32_e32 v73, vcc, 0, v153, vcc
	global_load_dwordx4 v[104:107], v[72:73], off offset:256
	v_add_co_u32_e32 v72, vcc, s12, v150
	s_waitcnt vmcnt(14)
	ds_write_b128 v214, v[64:67] offset:16384
	v_addc_co_u32_e32 v73, vcc, 0, v151, vcc
	global_load_dwordx4 v[108:111], v[72:73], off offset:256
	v_lshlrev_b32_e32 v72, 3, v74
	s_waitcnt vmcnt(14)
	ds_write_b128 v214, v[68:71] offset:49152
	s_waitcnt vmcnt(13)
	ds_write_b128 v214, v[76:79] offset:24576
	s_waitcnt vmcnt(12)
	ds_write_b128 v214, v[84:87] offset:57344
	v_add_u32_e32 v64, v175, v168
	v_add_u32_e32 v65, v169, v168
	v_sub_u32_e32 v112, 0x7f, v72
	ds_read_b64_tr_b16 v[72:73], v64
	ds_read_b64_tr_b16 v[80:81], v64 offset:8192
	ds_read_b64_tr_b16 v[88:89], v64 offset:16384
	ds_read_b64_tr_b16 v[92:93], v64 offset:24576
	ds_read_b64_tr_b16 v[74:75], v65 offset:1024
	ds_read_b64_tr_b16 v[82:83], v65 offset:9216
	ds_read_b64_tr_b16 v[90:91], v65 offset:17408
	ds_read_b64_tr_b16 v[94:95], v65 offset:25600
	v_cvt_f32_i32_e32 v124, v112
	s_add_i32 s43, s44, 1
	s_cmp_lt_u32 s43, s73
	s_cselect_b64 s[22:23], -1, 0
	s_cmp_ge_u32 s43, s73
	v_add_u32_e32 v125, v170, v171
	ds_read_b128 v[64:67], v125
	ds_read_b128 v[76:79], v125 offset:4096
	v_add_u32_e32 v126, v170, v172
	v_add_u32_e32 v127, v170, v173
	v_add_u32_e32 v140, v170, v174
	s_waitcnt lgkmcnt(1)
	v_and_b32_e32 v64, v64, v205
	v_and_b32_e32 v65, v65, v206
	v_and_b32_e32 v66, v66, v207
	v_and_b32_e32 v67, v67, v208
	s_nop 1
	v_mfma_f32_16x16x32_bf16 v[68:71], v[72:75], v[64:67], 0
	ds_read_b128 v[84:87], v125 offset:8192
	s_waitcnt lgkmcnt(1)
	v_and_b32_e32 v64, v76, v209
	v_and_b32_e32 v65, v77, v210
	v_and_b32_e32 v66, v78, v211
	v_and_b32_e32 v67, v79, v212
	s_nop 1
	v_mfma_f32_16x16x32_bf16 v[64:67], v[72:75], v[64:67], 0
	ds_read_b128 v[76:79], v126 offset:8192
	s_waitcnt lgkmcnt(0)
	v_and_b32_e32 v76, v76, v205
	v_mfma_f32_16x16x32_bf16 v[84:87], v[72:75], v[84:87], 0
	ds_read_b128 v[112:115], v125 offset:12288
	v_and_b32_e32 v77, v77, v206
	v_and_b32_e32 v78, v78, v207
	v_and_b32_e32 v79, v79, v208
	s_nop 1
	v_mfma_f32_16x16x32_bf16 v[76:79], v[80:83], v[76:79], v[84:87]
	s_nop 2
	ds_read_b128 v[84:87], v126 offset:12288
	s_waitcnt lgkmcnt(1)
	v_mfma_f32_16x16x32_bf16 v[112:115], v[72:75], v[112:115], 0
	ds_read_b128 v[116:119], v125 offset:16384
	s_waitcnt lgkmcnt(1)
	v_and_b32_e32 v84, v84, v209
	v_and_b32_e32 v85, v85, v210
	v_and_b32_e32 v86, v86, v211
	v_and_b32_e32 v87, v87, v212
	s_nop 1
	v_mfma_f32_16x16x32_bf16 v[84:87], v[80:83], v[84:87], v[112:115]
	s_nop 2
	ds_read_b128 v[112:115], v126 offset:16384
	s_waitcnt lgkmcnt(1)
	v_mfma_f32_16x16x32_bf16 v[116:119], v[72:75], v[116:119], 0
	ds_read_b128 v[120:123], v127 offset:16384
	s_waitcnt lgkmcnt(0)
	v_and_b32_e32 v120, v120, v205
	v_mfma_f32_16x16x32_bf16 v[112:115], v[80:83], v[112:115], v[116:119]
	v_and_b32_e32 v121, v121, v206
	v_and_b32_e32 v122, v122, v207
	v_and_b32_e32 v123, v123, v208
	s_nop 0
	ds_read_b128 v[116:119], v125 offset:20480
	v_mfma_f32_16x16x32_bf16 v[128:131], v[88:91], v[120:123], v[112:115]
	s_nop 2
	ds_read_b128 v[112:115], v126 offset:20480
	s_waitcnt lgkmcnt(1)
	v_mfma_f32_16x16x32_bf16 v[116:119], v[72:75], v[116:119], 0
	ds_read_b128 v[120:123], v127 offset:20480
	s_waitcnt lgkmcnt(0)
	v_and_b32_e32 v120, v120, v209
	v_mfma_f32_16x16x32_bf16 v[112:115], v[80:83], v[112:115], v[116:119]
	v_and_b32_e32 v121, v121, v210
	v_and_b32_e32 v122, v122, v211
	v_and_b32_e32 v123, v123, v212
	s_nop 0
	ds_read_b128 v[116:119], v125 offset:24576
	v_mfma_f32_16x16x32_bf16 v[132:135], v[88:91], v[120:123], v[112:115]
	s_nop 2
	ds_read_b128 v[112:115], v126 offset:24576
	s_waitcnt lgkmcnt(1)
	v_mfma_f32_16x16x32_bf16 v[116:119], v[72:75], v[116:119], 0
	ds_read_b128 v[120:123], v127 offset:24576
	s_waitcnt lgkmcnt(1)
	v_mfma_f32_16x16x32_bf16 v[112:115], v[80:83], v[112:115], v[116:119]
	s_nop 4
	ds_read_b128 v[116:119], v140 offset:24576
	s_waitcnt lgkmcnt(1)
	v_mfma_f32_16x16x32_bf16 v[112:115], v[88:91], v[120:123], v[112:115]
	ds_read_b128 v[120:123], v125 offset:28672
	s_waitcnt lgkmcnt(1)
	v_and_b32_e32 v116, v116, v205
	v_and_b32_e32 v117, v117, v206
	v_and_b32_e32 v118, v118, v207
	v_and_b32_e32 v119, v119, v208
	s_nop 1
	v_mfma_f32_16x16x32_bf16 v[136:139], v[92:95], v[116:119], v[112:115]
	s_nop 2
	ds_read_b128 v[112:115], v126 offset:28672
	s_waitcnt lgkmcnt(1)
	v_mfma_f32_16x16x32_bf16 v[116:119], v[72:75], v[120:123], 0
	ds_read_b128 v[120:123], v127 offset:28672
	s_waitcnt lgkmcnt(1)
	v_mfma_f32_16x16x32_bf16 v[112:115], v[80:83], v[112:115], v[116:119]
	s_nop 4
	ds_read_b128 v[116:119], v140 offset:28672
	s_waitcnt lgkmcnt(1)
	v_mfma_f32_16x16x32_bf16 v[112:115], v[88:91], v[120:123], v[112:115]
	s_waitcnt lgkmcnt(0)
; #define LAS __attribute__((address_space(3)))
; __device__ __forceinline__ void scan_phase(const Frame& F, const bf16_t* Q, const bf16_t* K, const bf16_t* V, const bf16_t* PB, bf16_t* OF, bf16_t* OB, int half) {
;     ...
;                       mattn_sfor<0, 20>([&](auto n_) { constexpr int n = decltype(n_)::value, pr = pv_pair(dir, n), it = pr >> 2, ks = pr & 3, dks = ks - (it >> 1);
;                           if constexpr (n + 1 < 20) { constexpr int nx = pv_pair(dir, n + 1); pwb[(n + 1) & 1] = *(const LAS u32x4*)(bPk[nx & 3] + 16 * (nx >> 2) * 256); }
;                           u32x4 pw = pwb[n & 1];
;                           if constexpr (dks == 0) { pw.x &= pmk[it & 1][0]; pw.y &= pmk[it & 1][1]; pw.z &= pmk[it & 1][2]; pw.w &= pmk[it & 1][3]; }
;                           Ot[it] = __builtin_amdgcn_mfma_f32_16x16x32_bf16(Vf[ks], __builtin_bit_cast(bf16x8, pw), Ot[it], 0, 0, 0);
;                           __builtin_amdgcn_sched_group_barrier(0x100, 1, 0); __builtin_amdgcn_sched_group_barrier(0x8, 1, 0); }); }
;                     __builtin_amdgcn_sched_barrier(0);
;                     { float fk = __builtin_amdgcn_exp2f(lg2 * (float)(dir ? 8 * quad_l : 127 - 8 * quad_l));
; #pragma unroll
;                       for (int ks = 0; ks < 4; ++ks) { u32x4 vw = __builtin_bit_cast(u32x4, Vf[ks]); float f = fk;
; #pragma unroll
;                         for (int e2 = 0; e2 < 4; ++e2) { const float f0 = f, f1 = f * gm1; f = f1 * gm1;
;                             vw[e2] = cvt_pk_bf16(bf_lo(vw[e2]) * f0, bf_hi(vw[e2]) * f1); }
;                         Vf[ks] = __builtin_bit_cast(bf16x8, vw); fk *= gm32; } }
;                 }
;                 __builtin_amdgcn_sched_barrier(0);
;                 {
;                     bf16x8 Rf[2];
; #pragma unroll
;                     for (int ks = 0; ks < 2; ++ks) { const f32x4 r0v = Rt[4 * p + 2 * ks], r1v = Rt[4 * p + 2 * ks + 1];
;                         const u32x4 wvv = {cvt_pk_bf16(r0v[0], r0v[1]), cvt_pk_bf16(r0v[2], r0v[3]), cvt_pk_bf16(r1v[0], r1v[1]), cvt_pk_bf16(r1v[2], r1v[3])};
;                         Rf[ks] = __builtin_bit_cast(bf16x8, wvv); }
;                     u32x4 qf[2][2];
;     ...
;                     SCAN_QREAD(0, 0);
; #pragma unroll
;                     for (int it = 0; it < 8; ++it) { if (it < 7) SCAN_QREAD((it + 1) & 1, it + 1);
; #pragma unroll
	v_and_b32_e32 v116, v116, v209
	v_and_b32_e32 v117, v117, v210
	v_and_b32_e32 v118, v118, v211
	v_and_b32_e32 v119, v119, v212
	s_nop 1
	v_mfma_f32_16x16x32_bf16 v[140:143], v[92:95], v[116:119], v[112:115]
	s_nop 2
	v_mul_f32_e32 v112, s54, v124
	v_exp_f32_e32 v112, v112
	v_lshlrev_b32_e32 v113, 16, v72
	v_and_b32_e32 v72, 0xffff0000, v72
	v_lshlrev_b32_e32 v116, 16, v73
	v_mul_f32_e32 v114, s18, v112
	v_mul_f32_e32 v113, v112, v113
	v_mul_f32_e32 v115, s18, v114
	v_mul_f32_e32 v72, v114, v72
	v_cvt_pk_bf16_f32 v72, v113, v72
	v_mul_f32_e32 v113, s18, v115
	v_mul_f32_e32 v114, s18, v113
	v_and_b32_e32 v73, 0xffff0000, v73
	v_mul_f32_e32 v115, v115, v116
	v_mul_f32_e32 v73, v113, v73
	v_mul_f32_e32 v113, s18, v114
	v_lshlrev_b32_e32 v116, 16, v74
	v_and_b32_e32 v74, 0xffff0000, v74
	v_cvt_pk_bf16_f32 v73, v115, v73
	v_mul_f32_e32 v115, s18, v113
	v_mul_f32_e32 v114, v114, v116
	v_mul_f32_e32 v74, v113, v74
	v_cvt_pk_bf16_f32 v74, v114, v74
	v_mul_f32_e32 v113, s18, v115
	v_lshlrev_b32_e32 v114, 16, v75
	v_and_b32_e32 v75, 0xffff0000, v75
	v_mul_f32_e32 v112, s36, v112
	v_mul_f32_e32 v114, v115, v114
	v_mul_f32_e32 v75, v113, v75
	v_mul_f32_e32 v113, s18, v112
	v_cvt_pk_bf16_f32 v75, v114, v75
	v_mul_f32_e32 v114, s18, v113
	v_lshlrev_b32_e32 v115, 16, v80
	v_and_b32_e32 v80, 0xffff0000, v80
	v_mul_f32_e32 v115, v112, v115
	v_mul_f32_e32 v80, v113, v80
	v_mul_f32_e32 v113, s18, v114
	v_cvt_pk_bf16_f32 v80, v115, v80
	v_mul_f32_e32 v115, s18, v113
	v_lshlrev_b32_e32 v116, 16, v81
	v_and_b32_e32 v81, 0xffff0000, v81
	v_mul_f32_e32 v114, v114, v116
	v_mul_f32_e32 v81, v113, v81
	v_mul_f32_e32 v113, s18, v115
	v_lshlrev_b32_e32 v116, 16, v82
	v_and_b32_e32 v82, 0xffff0000, v82
	v_cvt_pk_bf16_f32 v81, v114, v81
	v_mul_f32_e32 v114, s18, v113
	v_mul_f32_e32 v115, v115, v116
	v_mul_f32_e32 v82, v113, v82
	v_cvt_pk_bf16_f32 v82, v115, v82
	v_mul_f32_e32 v113, s18, v114
	v_lshlrev_b32_e32 v115, 16, v83
	v_and_b32_e32 v83, 0xffff0000, v83
	v_mul_f32_e32 v112, s36, v112
	v_mul_f32_e32 v114, v114, v115
	v_mul_f32_e32 v83, v113, v83
	v_mul_f32_e32 v113, s18, v112
	v_cvt_pk_bf16_f32 v83, v114, v83
	v_mul_f32_e32 v114, s18, v113
	v_lshlrev_b32_e32 v115, 16, v88
	v_and_b32_e32 v88, 0xffff0000, v88
	v_mul_f32_e32 v115, v112, v115
	v_mul_f32_e32 v88, v113, v88
	v_mul_f32_e32 v113, s18, v114
	v_cvt_pk_bf16_f32 v88, v115, v88
	v_mul_f32_e32 v115, s18, v113
	v_lshlrev_b32_e32 v116, 16, v89
	v_and_b32_e32 v89, 0xffff0000, v89
	v_mul_f32_e32 v114, v114, v116
	v_mul_f32_e32 v89, v113, v89
	v_mul_f32_e32 v113, s18, v115
	v_lshlrev_b32_e32 v116, 16, v90
	v_and_b32_e32 v90, 0xffff0000, v90
	v_cvt_pk_bf16_f32 v89, v114, v89
	v_mul_f32_e32 v114, s18, v113
	v_mul_f32_e32 v115, v115, v116
	v_mul_f32_e32 v90, v113, v90
	v_cvt_pk_bf16_f32 v90, v115, v90
	v_mul_f32_e32 v113, s18, v114
	v_lshlrev_b32_e32 v115, 16, v91
	v_and_b32_e32 v91, 0xffff0000, v91
	v_mul_f32_e32 v112, s36, v112
	v_mul_f32_e32 v114, v114, v115
	v_mul_f32_e32 v91, v113, v91
	v_mul_f32_e32 v113, s18, v112
	v_lshlrev_b32_e32 v115, 16, v92
	v_and_b32_e32 v92, 0xffff0000, v92
	v_cvt_pk_bf16_f32 v91, v114, v91
	v_mul_f32_e32 v114, s18, v113
	v_mul_f32_e32 v112, v112, v115
	v_mul_f32_e32 v92, v113, v92
	v_cvt_pk_bf16_f32 v92, v112, v92
	v_mul_f32_e32 v112, s18, v114
	v_mul_f32_e32 v113, s18, v112
	v_lshlrev_b32_e32 v115, 16, v93
	v_and_b32_e32 v93, 0xffff0000, v93
	v_mul_f32_e32 v114, v114, v115
	v_mul_f32_e32 v93, v112, v93
	v_mul_f32_e32 v112, s18, v113
	v_lshlrev_b32_e32 v115, 16, v94
	v_and_b32_e32 v94, 0xffff0000, v94
	v_cvt_pk_bf16_f32 v93, v114, v93
	v_mul_f32_e32 v114, s18, v112
	v_mul_f32_e32 v113, v113, v115
	v_mul_f32_e32 v94, v112, v94
	v_cvt_pk_bf16_f32 v94, v113, v94
	v_mul_f32_e32 v112, s18, v114
	v_lshlrev_b32_e32 v113, 16, v95
	v_and_b32_e32 v95, 0xffff0000, v95
	v_mul_f32_e32 v113, v114, v113
	v_mul_f32_e32 v95, v112, v95
	v_cvt_pk_bf16_f32 v95, v113, v95
	v_add_u32_e32 v217, v163, v164
	v_add_u32_e32 v218, v163, v165
	v_cvt_pk_bf16_f32 v194, v44, v45
	v_cvt_pk_bf16_f32 v195, v46, v47
	v_cvt_pk_bf16_f32 v196, v40, v41
	v_cvt_pk_bf16_f32 v197, v42, v43
	v_cvt_pk_bf16_f32 v222, v36, v37
	v_cvt_pk_bf16_f32 v223, v38, v39
	v_cvt_pk_bf16_f32 v224, v32, v33
	v_cvt_pk_bf16_f32 v225, v34, v35
	ds_read_b64 v[112:113], v217
	ds_read_b64 v[114:115], v218
	v_add_u32_e32 v219, v163, v166
	v_add_u32_e32 v220, v163, v167
	ds_read_b64 v[116:117], v219
	ds_read_b64 v[118:119], v220
	ds_read_b64 v[120:121], v217 offset:2048
	ds_read_b64 v[122:123], v218 offset:2048
	ds_read_b64 v[124:125], v219 offset:2048
	ds_read_b64 v[126:127], v220 offset:2048
	s_waitcnt lgkmcnt(6)
	v_mfma_f32_16x16x32_bf16 v[68:71], v[194:197], v[112:115], v[68:71]
	s_waitcnt lgkmcnt(4)
	v_mfma_f32_16x16x32_bf16 v[112:115], v[222:225], v[116:119], v[68:71]
	s_nop 5
	ds_read_b64 v[68:69], v217 offset:4096
	ds_read_b64 v[70:71], v218 offset:4096
	ds_read_b64 v[226:227], v219 offset:4096
	ds_read_b64 v[228:229], v220 offset:4096
	s_waitcnt lgkmcnt(6)
	v_mfma_f32_16x16x32_bf16 v[64:67], v[194:197], v[120:123], v[64:67]
	s_waitcnt lgkmcnt(4)
	v_mfma_f32_16x16x32_bf16 v[116:119], v[222:225], v[124:127], v[64:67]
	s_nop 5
	ds_read_b64 v[64:65], v217 offset:6144
	ds_read_b64 v[66:67], v218 offset:6144
	ds_read_b64 v[124:125], v219 offset:6144
	ds_read_b64 v[126:127], v220 offset:6144
	s_waitcnt lgkmcnt(6)
	v_mfma_f32_16x16x32_bf16 v[68:71], v[194:197], v[68:71], v[76:79]
	s_waitcnt lgkmcnt(4)
	v_mfma_f32_16x16x32_bf16 v[120:123], v[222:225], v[226:229], v[68:71]
	s_nop 5
	ds_read_b64 v[68:69], v217 offset:8192
	ds_read_b64 v[70:71], v218 offset:8192
	ds_read_b64 v[76:77], v219 offset:8192
	ds_read_b64 v[78:79], v220 offset:8192
	s_waitcnt lgkmcnt(6)
; __device__ __forceinline__ bf16x8 pack8(s16x4 lo, s16x4 hi) { return (bf16x8){lo[0], lo[1], lo[2], lo[3], hi[0], hi[1], hi[2], hi[3]}; }
; __device__ __forceinline__ void scan_phase(const Frame& F, const bf16_t* Q, const bf16_t* K, const bf16_t* V, const bf16_t* PB, bf16_t* OF, bf16_t* OB, int half) {
;     ...
;         unsigned pmk[2][4];
; #pragma unroll
;         for (int par = 0; par < 2; ++par) { int nk = 16 * par + l15 - 8 * quad + 1; nk = nk < 0 ? 0 : (nk > 8 ? 8 : nk);
; #pragma unroll
;     ...
;                     SCAN_QREAD(0, 0);
; #pragma unroll
;                     for (int it = 0; it < 8; ++it) { if (it < 7) SCAN_QREAD((it + 1) & 1, it + 1);
; #pragma unroll
;                         for (int ks = 0; ks < 2; ++ks) Ot[it] = __builtin_amdgcn_mfma_f32_16x16x32_bf16(Rf[ks], __builtin_bit_cast(bf16x8, qf[it & 1][ks]), Ot[it], 0, 0, 0); }
;     ...
;                     __builtin_amdgcn_sched_group_barrier(0x100, 4, 0);
;                     __builtin_amdgcn_sched_group_barrier(0x100, 4, 0); __builtin_amdgcn_sched_group_barrier(0x8, 2, 0);
;                     __builtin_amdgcn_sched_group_barrier(0x100, 4, 0); __builtin_amdgcn_sched_group_barrier(0x8, 2, 0);
;                     __builtin_amdgcn_sched_group_barrier(0x100, 4, 0); __builtin_amdgcn_sched_group_barrier(0x8, 2, 0);
;                     __builtin_amdgcn_sched_group_barrier(0x100, 4, 0); __builtin_amdgcn_sched_group_barrier(0x8, 2, 0);
;                     __builtin_amdgcn_sched_group_barrier(0x100, 4, 0); __builtin_amdgcn_sched_group_barrier(0x8, 2, 0);
;                     __builtin_amdgcn_sched_group_barrier(0x100, 4, 0); __builtin_amdgcn_sched_group_barrier(0x8, 2, 0);
;                     __builtin_amdgcn_sched_group_barrier(0x100, 4, 0); __builtin_amdgcn_sched_group_barrier(0x8, 2, 0);
;                     __builtin_amdgcn_sched_group_barrier(0x8, 2, 0);
;                 }
;                 __builtin_amdgcn_sched_barrier(0);
;                 { s16x4 kl[2][4], kh[2][4];
;     ...
;                 SCAN_KREAD(0, 0);
; #pragma unroll
;                 for (int mt = 0; mt < 4; ++mt) { if (mt < 3) SCAN_KREAD((mt + 1) & 1, mt + 1);
;                     f32x4 acc = Rt[4 * p + mt] * c1;
; #pragma unroll
;                     for (int ks = 0; ks < 4; ++ks) acc = __builtin_amdgcn_mfma_f32_16x16x32_bf16(pack8(kl[mt & 1][ks], kh[mt & 1][ks]), Vf[ks], acc, 0, 0, 0);
;                     Rt[4 * p + mt] = acc; }
	v_mfma_f32_16x16x32_bf16 v[64:67], v[194:197], v[64:67], v[84:87]
	s_waitcnt lgkmcnt(4)
	v_mfma_f32_16x16x32_bf16 v[124:127], v[222:225], v[124:127], v[64:67]
	s_nop 5
	ds_read_b64 v[64:65], v217 offset:10240
	ds_read_b64 v[66:67], v218 offset:10240
	ds_read_b64 v[84:85], v219 offset:10240
	ds_read_b64 v[86:87], v220 offset:10240
	s_waitcnt lgkmcnt(6)
	v_mfma_f32_16x16x32_bf16 v[68:71], v[194:197], v[68:71], v[128:131]
	s_waitcnt lgkmcnt(4)
	v_mfma_f32_16x16x32_bf16 v[128:131], v[222:225], v[76:79], v[68:71]
	s_nop 5
	ds_read_b64 v[68:69], v217 offset:12288
	ds_read_b64 v[70:71], v218 offset:12288
	ds_read_b64 v[76:77], v219 offset:12288
	ds_read_b64 v[78:79], v220 offset:12288
	s_waitcnt lgkmcnt(6)
	v_mfma_f32_16x16x32_bf16 v[64:67], v[194:197], v[64:67], v[132:135]
	s_waitcnt lgkmcnt(4)
	v_mfma_f32_16x16x32_bf16 v[132:135], v[222:225], v[84:87], v[64:67]
	s_nop 5
	ds_read_b64 v[64:65], v217 offset:14336
	ds_read_b64 v[66:67], v218 offset:14336
	ds_read_b64 v[84:85], v219 offset:14336
	ds_read_b64 v[86:87], v220 offset:14336
	s_waitcnt lgkmcnt(6)
	v_mfma_f32_16x16x32_bf16 v[68:71], v[194:197], v[68:71], v[136:139]
	s_waitcnt lgkmcnt(4)
	v_mfma_f32_16x16x32_bf16 v[136:139], v[222:225], v[76:79], v[68:71]
	s_waitcnt lgkmcnt(2)
	v_mfma_f32_16x16x32_bf16 v[64:67], v[194:197], v[64:67], v[140:143]
	s_waitcnt lgkmcnt(0)
	v_mfma_f32_16x16x32_bf16 v[140:143], v[222:225], v[84:87], v[64:67]
	v_add_u32_e32 v221, v182, v189
	v_add_u32_e32 v222, v182, v190
	s_nop 3
	ds_read_b64_tr_b16 v[64:65], v221 offset:32768
	ds_read_b64_tr_b16 v[66:67], v222 offset:33280
	ds_read_b64_tr_b16 v[68:69], v221 offset:36864
	ds_read_b64_tr_b16 v[70:71], v222 offset:37376
	v_mov_b32_e32 v145, v144
	ds_read_b64_tr_b16 v[76:77], v221 offset:40960
	ds_read_b64_tr_b16 v[78:79], v222 offset:41472
	v_add_u32_e32 v223, v182, v187
	v_add_u32_e32 v224, v182, v188
	v_mul_f32_e32 v46, v144, v46
	v_mul_f32_e32 v47, v145, v47
	v_mul_f32_e32 v44, v146, v44
	v_mul_f32_e32 v45, v147, v45
	ds_read_b64_tr_b16 v[84:85], v221 offset:45056
	ds_read_b64_tr_b16 v[86:87], v222 offset:45568
	ds_read_b64_tr_b16 v[194:195], v223 offset:32768
	ds_read_b64_tr_b16 v[196:197], v224 offset:33280
	ds_read_b64_tr_b16 v[228:229], v223 offset:36864
	ds_read_b64_tr_b16 v[230:231], v224 offset:37376
	ds_read_b64_tr_b16 v[232:233], v223 offset:40960
	ds_read_b64_tr_b16 v[234:235], v224 offset:41472
	ds_read_b64_tr_b16 v[236:237], v223 offset:45056
	ds_read_b64_tr_b16 v[238:239], v224 offset:45568
	s_waitcnt lgkmcnt(14)
	v_mfma_f32_16x16x32_bf16 v[44:47], v[64:67], v[72:75], v[44:47]
	v_add_u32_e32 v225, v182, v185
	v_add_u32_e32 v226, v182, v186
	v_mul_f32_e32 v42, v144, v42
	v_mul_f32_e32 v43, v145, v43
	s_waitcnt lgkmcnt(12)
	v_mfma_f32_16x16x32_bf16 v[44:47], v[68:71], v[80:83], v[44:47]
	v_mul_f32_e64 v40, v146, v40
	v_mul_f32_e64 v41, v147, v41
	v_add_u32_e32 v227, v182, v183
	v_mul_f32_e32 v38, v144, v38
	v_mul_f32_e32 v39, v145, v39
	s_waitcnt lgkmcnt(10)
	v_mfma_f32_16x16x32_bf16 v[44:47], v[76:79], v[88:91], v[44:47]
	v_mul_f32_e64 v36, v146, v36
	v_mul_f32_e64 v37, v147, v37
	v_mul_f32_e32 v34, v144, v34
	v_mul_f32_e32 v35, v145, v35
	v_mul_f32_e32 v32, v146, v32
	v_mul_f32_e32 v33, v147, v33
	s_waitcnt lgkmcnt(8)
	v_mfma_f32_16x16x32_bf16 v[44:47], v[84:87], v[92:95], v[44:47]
	ds_read_b64_tr_b16 v[64:65], v225 offset:32768
	ds_read_b64_tr_b16 v[66:67], v226 offset:33280
	ds_read_b64_tr_b16 v[68:69], v225 offset:36864
	ds_read_b64_tr_b16 v[70:71], v226 offset:37376
	ds_read_b64_tr_b16 v[76:77], v225 offset:40960
	ds_read_b64_tr_b16 v[78:79], v226 offset:41472
	ds_read_b64_tr_b16 v[84:85], v225 offset:45056
	ds_read_b64_tr_b16 v[86:87], v226 offset:45568
	s_waitcnt lgkmcnt(14)
	v_mfma_f32_16x16x32_bf16 v[40:43], v[194:197], v[72:75], v[40:43]
	s_waitcnt lgkmcnt(12)
	v_mfma_f32_16x16x32_bf16 v[40:43], v[228:231], v[80:83], v[40:43]
	v_add_u32_e32 v228, v182, v184
	s_waitcnt lgkmcnt(10)
	v_mfma_f32_16x16x32_bf16 v[40:43], v[232:235], v[88:91], v[40:43]
	s_waitcnt lgkmcnt(8)
	v_mfma_f32_16x16x32_bf16 v[40:43], v[236:239], v[92:95], v[40:43]
	ds_read_b64_tr_b16 v[194:195], v227 offset:32768
	ds_read_b64_tr_b16 v[196:197], v228 offset:33280
	ds_read_b64_tr_b16 v[230:231], v227 offset:36864
	ds_read_b64_tr_b16 v[232:233], v228 offset:37376
	ds_read_b64_tr_b16 v[234:235], v227 offset:40960
	ds_read_b64_tr_b16 v[236:237], v228 offset:41472
	ds_read_b64_tr_b16 v[238:239], v227 offset:45056
	ds_read_b64_tr_b16 v[240:241], v228 offset:45568
	s_waitcnt lgkmcnt(14)
	v_mfma_f32_16x16x32_bf16 v[36:39], v[64:67], v[72:75], v[36:39]
	s_waitcnt lgkmcnt(0)
	s_barrier
	s_waitcnt vmcnt(3)
	ds_write_b128 v214, v[96:99]
	s_waitcnt vmcnt(2)
	ds_write_b128 v214, v[100:103] offset:32768
	s_waitcnt lgkmcnt(14)
	v_mfma_f32_16x16x32_bf16 v[36:39], v[68:71], v[80:83], v[36:39]
	s_waitcnt vmcnt(1)
	ds_write_b128 v214, v[104:107] offset:8192
	s_waitcnt vmcnt(0)
	ds_write_b128 v214, v[108:111] offset:40960
	s_waitcnt lgkmcnt(14)
	v_mfma_f32_16x16x32_bf16 v[36:39], v[76:79], v[88:91], v[36:39]
	s_waitcnt lgkmcnt(12)
	v_mfma_f32_16x16x32_bf16 v[36:39], v[84:87], v[92:95], v[36:39]
	s_waitcnt lgkmcnt(10)
	v_mfma_f32_16x16x32_bf16 v[32:35], v[194:197], v[72:75], v[32:35]
	s_waitcnt lgkmcnt(8)
	v_mfma_f32_16x16x32_bf16 v[32:35], v[230:233], v[80:83], v[32:35]
	s_waitcnt lgkmcnt(6)
	v_mfma_f32_16x16x32_bf16 v[32:35], v[234:237], v[88:91], v[32:35]
	s_waitcnt lgkmcnt(4)
	v_mfma_f32_16x16x32_bf16 v[32:35], v[238:241], v[92:95], v[32:35]
	v_add_co_u32_e32 v64, vcc, 0x10800000, v152
	s_nop 1
	v_addc_co_u32_e32 v65, vcc, 0, v153, vcc
	v_add_co_u32_e32 v68, vcc, 0x4a900000, v150
	global_load_dwordx4 v[64:67], v[64:65], off offset:384
	s_nop 0
	v_addc_co_u32_e32 v69, vcc, 0, v151, vcc
	v_add_co_u32_e32 v76, vcc, 0x10840000, v152
	global_load_dwordx4 v[68:71], v[68:69], off offset:384
	s_nop 0
	v_addc_co_u32_e32 v77, vcc, 0, v153, vcc
	v_add_co_u32_e32 v84, vcc, 0x4a940000, v150
	global_load_dwordx4 v[76:79], v[76:77], off offset:384
	s_nop 0
	v_addc_co_u32_e32 v85, vcc, 0, v151, vcc
	global_load_dwordx4 v[84:87], v[84:85], off offset:384
	s_cbranch_scc1 .LBB0_990
; __device__ __forceinline__ void glds16u(const void* sbase, unsigned voff, unsigned lds_dst) { unsigned keep;
;     asm volatile("s_mov_b32 %0, m0\n\ts_mov_b32 m0, %3\n\ts_nop 0\n\tglobal_load_lds_dwordx4 %1, %2\n\ts_mov_b32 m0, %0" : "=&s"(keep) : "v"(voff), "s"(sbase), "s"(lds_dst) : "memory"); }
	s_add_i32 s12, s40, s44
	s_ashr_i32 s13, s12, 31
	s_lshl_b64 s[12:13], s[12:13], 18
	s_add_u32 s12, s38, s12
	s_mov_b32 s34, m0
	s_mov_b32 m0, s74
	s_nop 0
	global_load_lds_dwordx4 v154, s[30:31]
	s_mov_b32 m0, s34
	s_addc_u32 s13, s39, s13
	s_mov_b32 s34, m0
	s_mov_b32 m0, s75
	s_nop 0
	global_load_lds_dwordx4 v155, s[12:13]
	s_mov_b32 m0, s34
	s_nop 0
	s_mov_b32 s34, m0
	s_mov_b32 m0, s79
	s_nop 0
	global_load_lds_dwordx4 v156, s[30:31]
	s_mov_b32 m0, s34
	s_nop 0
	s_mov_b32 s34, m0
	s_mov_b32 m0, s80
	s_nop 0
	global_load_lds_dwordx4 v157, s[12:13]
	s_mov_b32 m0, s34
	s_nop 0
	s_mov_b32 s34, m0
	s_mov_b32 m0, s81
	s_nop 0
	global_load_lds_dwordx4 v158, s[30:31]
	s_mov_b32 m0, s34
	s_nop 0
	s_mov_b32 s34, m0
	s_mov_b32 m0, s82
	s_nop 0
	global_load_lds_dwordx4 v159, s[12:13]
	s_mov_b32 m0, s34
	s_nop 0
	s_mov_b32 s34, m0
	s_mov_b32 m0, s83
	s_nop 0
	global_load_lds_dwordx4 v215, s[30:31]
	s_mov_b32 m0, s34
	s_nop 0
	s_mov_b32 s34, m0
	s_mov_b32 m0, s84
	s_nop 0
	global_load_lds_dwordx4 v216, s[12:13]
	s_mov_b32 m0, s34
; __device__ __forceinline__ void scan_phase(const Frame& F, const bf16_t* Q, const bf16_t* K, const bf16_t* V, const bf16_t* PB, bf16_t* OF, bf16_t* OB, int half) {
;     ...
;                 {
;                     bf16x8 Rf[2];
; #pragma unroll
;                     for (int ks = 0; ks < 2; ++ks) { const f32x4 r0v = Rt[4 * p + 2 * ks], r1v = Rt[4 * p + 2 * ks + 1];
;                         const u32x4 wvv = {cvt_pk_bf16(r0v[0], r0v[1]), cvt_pk_bf16(r0v[2], r0v[3]), cvt_pk_bf16(r1v[0], r1v[1]), cvt_pk_bf16(r1v[2], r1v[3])};
;                         Rf[ks] = __builtin_bit_cast(bf16x8, wvv); }
;                     u32x4 qf[2][2];
;     ...
;                     SCAN_QREAD(0, 0);
; #pragma unroll
;                     for (int it = 0; it < 8; ++it) { if (it < 7) SCAN_QREAD((it + 1) & 1, it + 1);
; #pragma unroll
;                         for (int ks = 0; ks < 2; ++ks) Ot[it] = __builtin_amdgcn_mfma_f32_16x16x32_bf16(Rf[ks], __builtin_bit_cast(bf16x8, qf[it & 1][ks]), Ot[it], 0, 0, 0); }
;     ...
;                     __builtin_amdgcn_sched_group_barrier(0x100, 4, 0);
;                     __builtin_amdgcn_sched_group_barrier(0x100, 4, 0); __builtin_amdgcn_sched_group_barrier(0x8, 2, 0);
;                     __builtin_amdgcn_sched_group_barrier(0x100, 4, 0); __builtin_amdgcn_sched_group_barrier(0x8, 2, 0);
;                     __builtin_amdgcn_sched_group_barrier(0x100, 4, 0); __builtin_amdgcn_sched_group_barrier(0x8, 2, 0);
;                     __builtin_amdgcn_sched_group_barrier(0x100, 4, 0); __builtin_amdgcn_sched_group_barrier(0x8, 2, 0);
;                     __builtin_amdgcn_sched_group_barrier(0x100, 4, 0); __builtin_amdgcn_sched_group_barrier(0x8, 2, 0);
;                     __builtin_amdgcn_sched_group_barrier(0x100, 4, 0); __builtin_amdgcn_sched_group_barrier(0x8, 2, 0);
;                     __builtin_amdgcn_sched_group_barrier(0x100, 4, 0); __builtin_amdgcn_sched_group_barrier(0x8, 2, 0);
;                     __builtin_amdgcn_sched_group_barrier(0x8, 2, 0);
;                 }
;                 __builtin_amdgcn_sched_barrier(0);
;                 { s16x4 kl[2][4], kh[2][4];
;     ...
;                 SCAN_KREAD(0, 0);
; #pragma unroll
;                 for (int mt = 0; mt < 4; ++mt) { if (mt < 3) SCAN_KREAD((mt + 1) & 1, mt + 1);
;                     f32x4 acc = Rt[4 * p + mt] * c1;
; #pragma unroll
.LBB0_990:
	v_cvt_pk_bf16_f32 v194, v28, v29
	v_cvt_pk_bf16_f32 v195, v30, v31
	v_cvt_pk_bf16_f32 v196, v20, v21
	v_cvt_pk_bf16_f32 v197, v22, v23
	v_cvt_pk_bf16_f32 v230, v16, v17
	v_cvt_pk_bf16_f32 v231, v18, v19
	v_cvt_pk_bf16_f32 v232, v24, v25
	v_cvt_pk_bf16_f32 v233, v26, v27
	ds_read_b64 v[96:97], v217 offset:16384
	ds_read_b64 v[98:99], v218 offset:16384
	ds_read_b64 v[100:101], v219 offset:16384
	ds_read_b64 v[102:103], v220 offset:16384
	ds_read_b64 v[104:105], v217 offset:18432
	ds_read_b64 v[106:107], v218 offset:18432
	ds_read_b64 v[108:109], v219 offset:18432
	ds_read_b64 v[110:111], v220 offset:18432
	s_waitcnt lgkmcnt(6)
	v_mfma_f32_16x16x32_bf16 v[96:99], v[194:197], v[96:99], v[112:115]
	s_waitcnt lgkmcnt(4)
	v_mfma_f32_16x16x32_bf16 v[96:99], v[230:233], v[100:103], v[96:99]
	s_nop 0
	ds_read_b64 v[112:113], v217 offset:20480
	ds_read_b64 v[114:115], v218 offset:20480
	ds_read_b64 v[234:235], v219 offset:20480
	ds_read_b64 v[236:237], v220 offset:20480
	s_waitcnt lgkmcnt(6)
	v_mfma_f32_16x16x32_bf16 v[100:103], v[194:197], v[104:107], v[116:119]
	s_waitcnt lgkmcnt(4)
	v_mfma_f32_16x16x32_bf16 v[100:103], v[230:233], v[108:111], v[100:103]
	ds_read_b64 v[108:109], v217 offset:22528
	ds_read_b64 v[110:111], v218 offset:22528
	ds_read_b64 v[116:117], v219 offset:22528
	ds_read_b64 v[118:119], v220 offset:22528
	s_waitcnt lgkmcnt(6)
	v_mfma_f32_16x16x32_bf16 v[104:107], v[194:197], v[112:115], v[120:123]
	s_waitcnt lgkmcnt(4)
	v_mfma_f32_16x16x32_bf16 v[104:107], v[230:233], v[234:237], v[104:107]
	ds_read_b64 v[112:113], v217 offset:24576
	ds_read_b64 v[114:115], v218 offset:24576
	ds_read_b64 v[120:121], v219 offset:24576
	ds_read_b64 v[122:123], v220 offset:24576
	s_waitcnt lgkmcnt(6)
	v_mfma_f32_16x16x32_bf16 v[108:111], v[194:197], v[108:111], v[124:127]
	s_waitcnt lgkmcnt(4)
	v_mfma_f32_16x16x32_bf16 v[108:111], v[230:233], v[116:119], v[108:111]
	ds_read_b64 v[116:117], v217 offset:26624
	ds_read_b64 v[118:119], v218 offset:26624
	ds_read_b64 v[124:125], v219 offset:26624
	ds_read_b64 v[126:127], v220 offset:26624
	s_waitcnt lgkmcnt(6)
	v_mfma_f32_16x16x32_bf16 v[112:115], v[194:197], v[112:115], v[128:131]
	s_waitcnt lgkmcnt(4)
	v_mfma_f32_16x16x32_bf16 v[112:115], v[230:233], v[120:123], v[112:115]
	ds_read_b64 v[120:121], v217 offset:28672
	ds_read_b64 v[122:123], v218 offset:28672
	ds_read_b64 v[128:129], v219 offset:28672
	ds_read_b64 v[130:131], v220 offset:28672
	s_waitcnt lgkmcnt(6)
	v_mfma_f32_16x16x32_bf16 v[116:119], v[194:197], v[116:119], v[132:135]
	s_waitcnt lgkmcnt(4)
	v_mfma_f32_16x16x32_bf16 v[116:119], v[230:233], v[124:127], v[116:119]
	ds_read_b64 v[124:125], v217 offset:30720
	ds_read_b64 v[126:127], v218 offset:30720
	ds_read_b64 v[132:133], v219 offset:30720
	ds_read_b64 v[134:135], v220 offset:30720
	s_waitcnt lgkmcnt(6)
	v_mfma_f32_16x16x32_bf16 v[120:123], v[194:197], v[120:123], v[136:139]
	s_waitcnt lgkmcnt(4)
	v_mfma_f32_16x16x32_bf16 v[120:123], v[230:233], v[128:131], v[120:123]
	s_waitcnt lgkmcnt(2)
	v_mfma_f32_16x16x32_bf16 v[124:127], v[194:197], v[124:127], v[140:143]
	s_waitcnt lgkmcnt(0)
	v_mfma_f32_16x16x32_bf16 v[124:127], v[230:233], v[132:135], v[124:127]
	ds_read_b64_tr_b16 v[128:129], v221 offset:49152
	ds_read_b64_tr_b16 v[130:131], v222 offset:49664
	ds_read_b64_tr_b16 v[132:133], v221 offset:53248
	ds_read_b64_tr_b16 v[134:135], v222 offset:53760
	ds_read_b64_tr_b16 v[136:137], v221 offset:57344
	ds_read_b64_tr_b16 v[138:139], v222 offset:57856
	v_mul_f32_e32 v30, v144, v30
	v_mul_f32_e32 v31, v145, v31
	v_mul_f32_e32 v28, v146, v28
	v_mul_f32_e32 v29, v147, v29
	ds_read_b64_tr_b16 v[140:141], v221 offset:61440
	ds_read_b64_tr_b16 v[142:143], v222 offset:61952
	ds_read_b64_tr_b16 v[194:195], v223 offset:49152
	ds_read_b64_tr_b16 v[196:197], v224 offset:49664
	ds_read_b64_tr_b16 v[230:231], v223 offset:53248
	ds_read_b64_tr_b16 v[232:233], v224 offset:53760
	ds_read_b64_tr_b16 v[234:235], v223 offset:57344
	ds_read_b64_tr_b16 v[236:237], v224 offset:57856
	ds_read_b64_tr_b16 v[238:239], v223 offset:61440
	ds_read_b64_tr_b16 v[240:241], v224 offset:61952
	s_waitcnt lgkmcnt(14)
	v_mfma_f32_16x16x32_bf16 v[28:31], v[128:131], v[72:75], v[28:31]
	v_mul_f32_e64 v22, v144, v22
	v_mul_f32_e64 v23, v145, v23
	v_mul_f32_e32 v20, v146, v20
	v_mul_f32_e32 v21, v147, v21
	v_mul_f32_e32 v18, v144, v18
	v_mul_f32_e32 v19, v145, v19
	s_waitcnt lgkmcnt(12)
	v_mfma_f32_16x16x32_bf16 v[28:31], v[132:135], v[80:83], v[28:31]
	v_mul_f32_e64 v16, v146, v16
	v_mul_f32_e64 v17, v147, v17
	v_mul_f32_e32 v26, v144, v26
	v_mul_f32_e32 v27, v145, v27
	v_mul_f32_e32 v24, v146, v24
	v_mul_f32_e32 v25, v147, v25
	s_waitcnt lgkmcnt(10)
	v_mfma_f32_16x16x32_bf16 v[28:31], v[136:139], v[88:91], v[28:31]
	s_andn2_b64 vcc, exec, s[22:23]
	s_waitcnt lgkmcnt(8)
	v_mfma_f32_16x16x32_bf16 v[28:31], v[140:143], v[92:95], v[28:31]
	ds_read_b64_tr_b16 v[128:129], v225 offset:49152
	ds_read_b64_tr_b16 v[130:131], v226 offset:49664
	ds_read_b64_tr_b16 v[132:133], v225 offset:53248
	ds_read_b64_tr_b16 v[134:135], v226 offset:53760
	ds_read_b64_tr_b16 v[136:137], v225 offset:57344
	ds_read_b64_tr_b16 v[138:139], v226 offset:57856
	ds_read_b64_tr_b16 v[140:141], v225 offset:61440
	ds_read_b64_tr_b16 v[142:143], v226 offset:61952
	s_waitcnt lgkmcnt(14)
	v_mfma_f32_16x16x32_bf16 v[20:23], v[194:197], v[72:75], v[20:23]
	s_waitcnt lgkmcnt(12)
	v_mfma_f32_16x16x32_bf16 v[20:23], v[230:233], v[80:83], v[20:23]
	s_waitcnt lgkmcnt(10)
	v_mfma_f32_16x16x32_bf16 v[20:23], v[234:237], v[88:91], v[20:23]
	s_waitcnt lgkmcnt(8)
	v_mfma_f32_16x16x32_bf16 v[20:23], v[238:241], v[92:95], v[20:23]
	ds_read_b64_tr_b16 v[194:195], v227 offset:49152
	ds_read_b64_tr_b16 v[196:197], v228 offset:49664
	ds_read_b64_tr_b16 v[230:231], v227 offset:53248
	ds_read_b64_tr_b16 v[232:233], v228 offset:53760
	ds_read_b64_tr_b16 v[234:235], v227 offset:57344
	ds_read_b64_tr_b16 v[236:237], v228 offset:57856
	ds_read_b64_tr_b16 v[238:239], v227 offset:61440
	ds_read_b64_tr_b16 v[240:241], v228 offset:61952
	s_waitcnt lgkmcnt(14)
	v_mfma_f32_16x16x32_bf16 v[16:19], v[128:131], v[72:75], v[16:19]
	s_waitcnt lgkmcnt(0)
	s_barrier
	v_cndmask_b32_e64 v128, 0, 1, s[22:23]
	v_cmp_ne_u32_e64 s[34:35], 1, v128
	s_waitcnt lgkmcnt(12)
	v_mfma_f32_16x16x32_bf16 v[16:19], v[132:135], v[80:83], v[16:19]
	s_cbranch_vccnz .Lscan1_nodma
	s_waitcnt vmcnt(8)
	s_branch .Lscan1_wdone

; __device__ __forceinline__ void scan_phase(const Frame& F, const bf16_t* Q, const bf16_t* K, const bf16_t* V, const bf16_t* PB, bf16_t* OF, bf16_t* OB, int half) {
;     ...
;                 {
;                     bf16x8 Rf[2];
; #pragma unroll
;                     for (int ks = 0; ks < 2; ++ks) { const f32x4 r0v = Rt[4 * p + 2 * ks], r1v = Rt[4 * p + 2 * ks + 1];
;                         const u32x4 wvv = {cvt_pk_bf16(r0v[0], r0v[1]), cvt_pk_bf16(r0v[2], r0v[3]), cvt_pk_bf16(r1v[0], r1v[1]), cvt_pk_bf16(r1v[2], r1v[3])};
;                         Rf[ks] = __builtin_bit_cast(bf16x8, wvv); }
;                     u32x4 qf[2][2];
;     ...
;                     SCAN_QREAD(0, 0);
; #pragma unroll
;                     for (int it = 0; it < 8; ++it) { if (it < 7) SCAN_QREAD((it + 1) & 1, it + 1);
; #pragma unroll
;                         for (int ks = 0; ks < 2; ++ks) Ot[it] = __builtin_amdgcn_mfma_f32_16x16x32_bf16(Rf[ks], __builtin_bit_cast(bf16x8, qf[it & 1][ks]), Ot[it], 0, 0, 0); }
;     ...
;                     __builtin_amdgcn_sched_group_barrier(0x100, 4, 0);
;                     __builtin_amdgcn_sched_group_barrier(0x100, 4, 0); __builtin_amdgcn_sched_group_barrier(0x8, 2, 0);
;                     __builtin_amdgcn_sched_group_barrier(0x100, 4, 0); __builtin_amdgcn_sched_group_barrier(0x8, 2, 0);
;                     __builtin_amdgcn_sched_group_barrier(0x100, 4, 0); __builtin_amdgcn_sched_group_barrier(0x8, 2, 0);
;                     __builtin_amdgcn_sched_group_barrier(0x100, 4, 0); __builtin_amdgcn_sched_group_barrier(0x8, 2, 0);
;                     __builtin_amdgcn_sched_group_barrier(0x100, 4, 0); __builtin_amdgcn_sched_group_barrier(0x8, 2, 0);
;                     __builtin_amdgcn_sched_group_barrier(0x100, 4, 0); __builtin_amdgcn_sched_group_barrier(0x8, 2, 0);
;                     __builtin_amdgcn_sched_group_barrier(0x100, 4, 0); __builtin_amdgcn_sched_group_barrier(0x8, 2, 0);
;                     __builtin_amdgcn_sched_group_barrier(0x8, 2, 0);
;                 }
;                 __builtin_amdgcn_sched_barrier(0);
;                 { s16x4 kl[2][4], kh[2][4];
;     ...
;                 SCAN_KREAD(0, 0);
; #pragma unroll
;                 for (int mt = 0; mt < 4; ++mt) { if (mt < 3) SCAN_KREAD((mt + 1) & 1, mt + 1);
;                     f32x4 acc = Rt[4 * p + mt] * c1;
; #pragma unroll
.LBB0_992:
	v_cvt_pk_bf16_f32 v128, v12, v13
	v_cvt_pk_bf16_f32 v129, v14, v15
	v_cvt_pk_bf16_f32 v130, v8, v9
	v_cvt_pk_bf16_f32 v131, v10, v11
	v_cvt_pk_bf16_f32 v132, v4, v5
	v_cvt_pk_bf16_f32 v133, v6, v7
	v_cvt_pk_bf16_f32 v134, v0, v1
	v_cvt_pk_bf16_f32 v135, v2, v3
	ds_read_b64 v[136:137], v217
	ds_read_b64 v[138:139], v218
	ds_read_b64 v[140:141], v219
	ds_read_b64 v[142:143], v220
	ds_read_b64 v[194:195], v217 offset:2048
	ds_read_b64 v[196:197], v218 offset:2048
	ds_read_b64 v[230:231], v219 offset:2048
	ds_read_b64 v[232:233], v220 offset:2048
	s_waitcnt lgkmcnt(6)
	v_mfma_f32_16x16x32_bf16 v[96:99], v[128:131], v[136:139], v[96:99]
	s_waitcnt lgkmcnt(4)
	v_mfma_f32_16x16x32_bf16 v[96:99], v[132:135], v[140:143], v[96:99]
	ds_read_b64 v[136:137], v217 offset:4096
	ds_read_b64 v[138:139], v218 offset:4096
	ds_read_b64 v[140:141], v219 offset:4096
	ds_read_b64 v[142:143], v220 offset:4096
	s_waitcnt lgkmcnt(6)
	v_mfma_f32_16x16x32_bf16 v[100:103], v[128:131], v[194:197], v[100:103]
	s_waitcnt lgkmcnt(4)
	v_mfma_f32_16x16x32_bf16 v[100:103], v[132:135], v[230:233], v[100:103]
	ds_read_b64 v[194:195], v217 offset:6144
	ds_read_b64 v[196:197], v218 offset:6144
	ds_read_b64 v[230:231], v219 offset:6144
	ds_read_b64 v[232:233], v220 offset:6144
	s_waitcnt lgkmcnt(6)
	v_mfma_f32_16x16x32_bf16 v[104:107], v[128:131], v[136:139], v[104:107]
	s_waitcnt lgkmcnt(4)
	v_mfma_f32_16x16x32_bf16 v[104:107], v[132:135], v[140:143], v[104:107]
	ds_read_b64 v[136:137], v217 offset:8192
	ds_read_b64 v[138:139], v218 offset:8192
	ds_read_b64 v[140:141], v219 offset:8192
	ds_read_b64 v[142:143], v220 offset:8192
	s_waitcnt lgkmcnt(6)
	v_mfma_f32_16x16x32_bf16 v[108:111], v[128:131], v[194:197], v[108:111]
	s_waitcnt lgkmcnt(4)
	v_mfma_f32_16x16x32_bf16 v[108:111], v[132:135], v[230:233], v[108:111]
	ds_read_b64 v[194:195], v217 offset:10240
	ds_read_b64 v[196:197], v218 offset:10240
	ds_read_b64 v[230:231], v219 offset:10240
	ds_read_b64 v[232:233], v220 offset:10240
	s_waitcnt lgkmcnt(6)
	v_mfma_f32_16x16x32_bf16 v[112:115], v[128:131], v[136:139], v[112:115]
	s_waitcnt lgkmcnt(4)
	v_mfma_f32_16x16x32_bf16 v[112:115], v[132:135], v[140:143], v[112:115]
	ds_read_b64 v[136:137], v217 offset:12288
	ds_read_b64 v[138:139], v218 offset:12288
	ds_read_b64 v[140:141], v219 offset:12288
	ds_read_b64 v[142:143], v220 offset:12288
	s_waitcnt lgkmcnt(6)
	v_mfma_f32_16x16x32_bf16 v[116:119], v[128:131], v[194:197], v[116:119]
	s_waitcnt lgkmcnt(4)
	v_mfma_f32_16x16x32_bf16 v[116:119], v[132:135], v[230:233], v[116:119]
	ds_read_b64 v[194:195], v217 offset:14336
	ds_read_b64 v[196:197], v218 offset:14336
	ds_read_b64 v[230:231], v219 offset:14336
	ds_read_b64 v[232:233], v220 offset:14336
	s_waitcnt lgkmcnt(6)
	v_mfma_f32_16x16x32_bf16 v[120:123], v[128:131], v[136:139], v[120:123]
	s_waitcnt lgkmcnt(4)
	v_mfma_f32_16x16x32_bf16 v[120:123], v[132:135], v[140:143], v[120:123]
	s_waitcnt lgkmcnt(2)
	v_mfma_f32_16x16x32_bf16 v[124:127], v[128:131], v[194:197], v[124:127]
	s_waitcnt lgkmcnt(0)
	v_mfma_f32_16x16x32_bf16 v[124:127], v[132:135], v[230:233], v[124:127]
	ds_read_b64_tr_b16 v[128:129], v221 offset:32768
	ds_read_b64_tr_b16 v[130:131], v222 offset:33280
	ds_read_b64_tr_b16 v[132:133], v221 offset:36864
	ds_read_b64_tr_b16 v[134:135], v222 offset:37376
	v_mov_b32_e32 v145, v144
	ds_read_b64_tr_b16 v[136:137], v221 offset:40960
	ds_read_b64_tr_b16 v[138:139], v222 offset:41472
	v_mul_f32_e32 v14, v144, v14
	v_mul_f32_e32 v15, v145, v15
	v_mul_f32_e32 v12, v146, v12
	v_mul_f32_e32 v13, v147, v13
	ds_read_b64_tr_b16 v[140:141], v221 offset:45056
	ds_read_b64_tr_b16 v[142:143], v222 offset:45568
	ds_read_b64_tr_b16 v[194:195], v223 offset:32768
	ds_read_b64_tr_b16 v[196:197], v224 offset:33280
	ds_read_b64_tr_b16 v[230:231], v223 offset:36864
	ds_read_b64_tr_b16 v[232:233], v224 offset:37376
	ds_read_b64_tr_b16 v[234:235], v223 offset:40960
	ds_read_b64_tr_b16 v[236:237], v224 offset:41472
	ds_read_b64_tr_b16 v[238:239], v223 offset:45056
	ds_read_b64_tr_b16 v[240:241], v224 offset:45568
	s_waitcnt lgkmcnt(14)
	v_mfma_f32_16x16x32_bf16 v[12:15], v[128:131], v[72:75], v[12:15]
	v_mul_f32_e64 v10, v144, v10
	v_mul_f32_e64 v11, v145, v11
	v_mul_f32_e32 v8, v146, v8
	v_mul_f32_e32 v9, v147, v9
	v_mul_f32_e32 v6, v144, v6
	v_mul_f32_e32 v7, v145, v7
	s_waitcnt lgkmcnt(12)
	v_mfma_f32_16x16x32_bf16 v[12:15], v[132:135], v[80:83], v[12:15]
	v_mul_f32_e64 v4, v146, v4
	v_mul_f32_e64 v5, v147, v5
	v_mul_f32_e32 v2, v144, v2
	v_mul_f32_e32 v3, v145, v3
	v_mul_f32_e32 v0, v146, v0
	v_mul_f32_e32 v1, v147, v1
	s_waitcnt lgkmcnt(10)
	v_mfma_f32_16x16x32_bf16 v[12:15], v[136:139], v[88:91], v[12:15]
	s_and_b64 vcc, exec, s[34:35]
	s_waitcnt lgkmcnt(8)
	v_mfma_f32_16x16x32_bf16 v[12:15], v[140:143], v[92:95], v[12:15]
	ds_read_b64_tr_b16 v[128:129], v225 offset:32768
	ds_read_b64_tr_b16 v[130:131], v226 offset:33280
	ds_read_b64_tr_b16 v[132:133], v225 offset:36864
	ds_read_b64_tr_b16 v[134:135], v226 offset:37376
	ds_read_b64_tr_b16 v[136:137], v225 offset:40960
	ds_read_b64_tr_b16 v[138:139], v226 offset:41472
	ds_read_b64_tr_b16 v[140:141], v225 offset:45056
	ds_read_b64_tr_b16 v[142:143], v226 offset:45568
	s_waitcnt lgkmcnt(14)
	v_mfma_f32_16x16x32_bf16 v[8:11], v[194:197], v[72:75], v[8:11]
	s_waitcnt lgkmcnt(12)
	v_mfma_f32_16x16x32_bf16 v[8:11], v[230:233], v[80:83], v[8:11]
	s_waitcnt lgkmcnt(10)
	v_mfma_f32_16x16x32_bf16 v[8:11], v[234:237], v[88:91], v[8:11]
	s_waitcnt lgkmcnt(8)
	v_mfma_f32_16x16x32_bf16 v[8:11], v[238:241], v[92:95], v[8:11]
	ds_read_b64_tr_b16 v[194:195], v227 offset:32768
	ds_read_b64_tr_b16 v[196:197], v228 offset:33280
	ds_read_b64_tr_b16 v[230:231], v227 offset:36864
	ds_read_b64_tr_b16 v[232:233], v228 offset:37376
	ds_read_b64_tr_b16 v[234:235], v227 offset:40960
	ds_read_b64_tr_b16 v[236:237], v228 offset:41472
	ds_read_b64_tr_b16 v[238:239], v227 offset:45056
	ds_read_b64_tr_b16 v[240:241], v228 offset:45568
	s_waitcnt lgkmcnt(14)
	v_mfma_f32_16x16x32_bf16 v[4:7], v[128:131], v[72:75], v[4:7]
	s_waitcnt lgkmcnt(0)
	s_barrier
; __device__ __forceinline__ bf16x8 pack8(s16x4 lo, s16x4 hi) { return (bf16x8){lo[0], lo[1], lo[2], lo[3], hi[0], hi[1], hi[2], hi[3]}; }
; #define SCAN_BAR() asm volatile("s_waitcnt lgkmcnt(0)\n\ts_barrier" ::: "memory")
; #define SCAN_LOAD_QK(cc, pq) do { const size_t u0_ = (rb + (size_t)(cc) * 128) * 2048 + head * 256 + (pq) * 64;     \
;             _Pragma("unroll") for (int ii = 0; ii < 2; ++ii) { rq[ii] = *(const GAS u32x4*)(Q + u0_ + (size_t)ii * 64 * 2048 + lqk_l); rk[ii] = *(const GAS u32x4*)(K + u0_ + (size_t)ii * 64 * 2048 + lqk_l); } } while (0)
; __device__ __forceinline__ void scan_phase(const Frame& F, const bf16_t* Q, const bf16_t* K, const bf16_t* V, const bf16_t* PB, bf16_t* OF, bf16_t* OB, int half) {
;     ...
;         unsigned pmk[2][4];
; #pragma unroll
;         for (int par = 0; par < 2; ++par) { int nk = 16 * par + l15 - 8 * quad + 1; nk = nk < 0 ? 0 : (nk > 8 ? 8 : nk);
; #pragma unroll
;             for (int d_ = 0; d_ < 4; ++d_) { const unsigned mf = ((2 * d_ < nk) ? 0xffffu : 0u) | ((2 * d_ + 1 < nk) ? 0xffff0000u : 0u); pmk[par][d_] = dir ? ~mf : mf; } }
;         { const int c0 = dir ? nchunk - 1 : 0; SCAN_DMA_VP(c0); SCAN_LOAD_QK(c0, 0); SCAN_WRITE_QK(0); SCAN_LOAD_QK(c0, 1); }
;         SCAN_BAR();
;         for (int s = 0; s < nchunk; ++s) {
;             const int c = dir ? nchunk - 1 - s : s, cn = dir ? nchunk - 2 - s : s + 1; const size_t r0 = rb + (size_t)c * 128; const bool more = s + 1 < nchunk;
;             f32x4 Ot[8]; bf16x8 Vf[4];
; #pragma unroll
;             for (int i = 0; i < 8; ++i) Ot[i] = (f32x4){0.f, 0.f, 0.f, 0.f};
;             int quad_l = quad, l15_l = l15; asm volatile("" : "+v"(quad_l), "+v"(l15_l));
; #pragma unroll
;             for (int p = 0; p < 4; ++p) {
;                 if (p < 3 || more) SCAN_WRITE_QK((p + 1) & 1);
;                 if (p == 1 && more) SCAN_DMA_VP(cn);
;                 if (p < 2) SCAN_LOAD_QK(c, p + 2); else if (more) SCAN_LOAD_QK(cn, p - 2);
;     ...
;                 for (int mt = 0; mt < 4; ++mt) { if (mt < 3) SCAN_KREAD((mt + 1) & 1, mt + 1);
;                     f32x4 acc = Rt[4 * p + mt] * c1;
; #pragma unroll
;                     for (int ks = 0; ks < 4; ++ks) acc = __builtin_amdgcn_mfma_f32_16x16x32_bf16(pack8(kl[mt & 1][ks], kh[mt & 1][ks]), Vf[ks], acc, 0, 0, 0);
;                     Rt[4 * p + mt] = acc; }
	s_waitcnt lgkmcnt(12)
	v_mfma_f32_16x16x32_bf16 v[4:7], v[132:135], v[80:83], v[4:7]
	s_waitcnt lgkmcnt(10)
	v_mfma_f32_16x16x32_bf16 v[4:7], v[136:139], v[88:91], v[4:7]
	s_waitcnt lgkmcnt(8)
	v_mfma_f32_16x16x32_bf16 v[4:7], v[140:143], v[92:95], v[4:7]
	s_waitcnt lgkmcnt(6)
	v_mfma_f32_16x16x32_bf16 v[0:3], v[194:197], v[72:75], v[0:3]
	s_waitcnt lgkmcnt(4)
	v_mfma_f32_16x16x32_bf16 v[0:3], v[230:233], v[80:83], v[0:3]
	s_waitcnt lgkmcnt(2)
	v_mfma_f32_16x16x32_bf16 v[0:3], v[234:237], v[88:91], v[0:3]
	s_waitcnt lgkmcnt(0)
	v_mfma_f32_16x16x32_bf16 v[0:3], v[238:241], v[92:95], v[0:3]
	s_cbranch_vccnz .LBB0_987
	s_waitcnt vmcnt(3)
	ds_write_b128 v214, v[64:67]
	s_waitcnt vmcnt(2)
	ds_write_b128 v214, v[68:71] offset:32768
	s_waitcnt vmcnt(1)
	ds_write_b128 v214, v[76:79] offset:8192
	s_waitcnt vmcnt(0)
	ds_write_b128 v214, v[84:87] offset:40960
	v_add_co_u32_e32 v64, vcc, 0x10880000, v152
	s_nop 1
	v_addc_co_u32_e32 v65, vcc, 0, v153, vcc
	v_add_co_u32_e32 v68, vcc, 0x4a980000, v150
	global_load_dwordx4 v[64:67], v[64:65], off offset:128
	s_nop 0
	v_addc_co_u32_e32 v69, vcc, 0, v151, vcc
	v_add_co_u32_e32 v76, vcc, 0x108c0000, v152
	global_load_dwordx4 v[68:71], v[68:69], off offset:128
	s_nop 0
	v_addc_co_u32_e32 v77, vcc, 0, v153, vcc
	v_add_co_u32_e32 v84, vcc, 0x4a9c0000, v150
	global_load_dwordx4 v[76:79], v[76:77], off offset:128
	s_nop 0
	v_addc_co_u32_e32 v85, vcc, 0, v151, vcc
	global_load_dwordx4 v[84:87], v[84:85], off offset:128
	s_branch .LBB0_987
